# adds: all four GEMM K-loops (in-proj, fp8 gate, branch, out) address their LDS-DMA loads as SGPR base + 32-bit lane offset: no per-load VALU address arithmetic
# speedup vs baseline: 1.0105x; 1.0048x over previous
; #define PG8_STAGE(bufoff, gbase, voff) do { unsigned _g = (gbase); asm volatile("" : "+s"(_g));   _Pragma("unroll") for (int _i = 0; _i < 2; ++_i) \
;         __builtin_amdgcn_global_load_lds((const unsigned*)(wsb + (size_t)(unsigned)(_g + (voff)[_i])), (LAS unsigned*)(lds + (bufoff) + ldsw + _i * 8192), 16, 0, 0); } while (0)
; #define PG8_WAIT_V(n) asm volatile("s_waitcnt vmcnt(" #n ")" ::: "memory")
; #define PG8_WAIT_L(n) asm volatile("s_waitcnt lgkmcnt(" #n ")" ::: "memory")
; #define PG8_BAR __builtin_amdgcn_s_barrier()
; #define PG8_SCHED __builtin_amdgcn_sched_barrier(0)
;     ...
;             const unsigned a1 = cA + (unsigned)(t + 1) * kstep;
;             const unsigned a2 = last ? nA : cA + (unsigned)(t + 2) * kstep, b2 = last ? nB : cB + (unsigned)(t + 2) * kstep;
;             const unsigned a3 = a2 + kstep, b3 = b2 + kstep;
;             if constexpr (SP2) {
;             PG8_LDB(B0, 0, 0); PG8_LDB(B1, 0, 1); PG8_SCHED; PG8_LDA(At, 0, 0); PG8_STAGE(PG8_SA(1, 1), a1 + hstep, voffA);
;             PG8_WAIT_V(8); PG8_WAIT_L(0); PG8_BAR; PG8_MMA(0, 0, At, B0); PG8_MMA(0, 1, At, B1); PG8_BAR; PG8_SCHED;
;             PG8_LDA(At, 0, 1); PG8_STAGE(PG8_SB(0, 0), b2, voffB); PG8_STAGE(PG8_SB(0, 1), b2 + hstep, voffB); PG8_STAGE(PG8_SA(0, 0), a2, voffA);
;             PG8_WAIT_V(8); PG8_WAIT_L(0); PG8_BAR; PG8_MMA(1, 0, At, B0); PG8_MMA(1, 1, At, B1); PG8_BAR; PG8_SCHED;
.LBB0_279:
	v_readfirstlane_b32 s100, v130
	v_readfirstlane_b32 s101, v131
	s_nop 1
	s_sub_u32 s100, s100, 0x10000000
	s_subb_u32 s101, s101, 0
	s_add_i32 s11, s8, 0xfff00080
	s_cmp_eq_u32 s10, 60
	s_cselect_b32 s83, s4, s11
	s_cselect_b32 s82, s5, s9
	s_add_i32 s84, 0, 0x10000
	v_add_u32_e32 v0, s84, v152
	s_add_i32 s96, 0, 0x14000
	ds_read_b128 v[138:141], v0
	ds_read_b128 v[142:145], v0 offset:1024
	ds_read_b128 v[154:157], v0 offset:2048
	ds_read_b128 v[158:161], v0 offset:3072
	v_add_u32_e32 v0, s96, v152
	ds_read_b128 v[162:165], v0
	ds_read_b128 v[166:169], v0 offset:1024
	ds_read_b128 v[170:173], v0 offset:2048
	ds_read_b128 v[174:177], v0 offset:3072
	s_add_i32 s11, s83, 0x80
	s_mov_b32 s97, s8
	ds_read_b128 v[178:181], v153
	ds_read_b128 v[182:185], v153 offset:1024
	ds_read_b128 v[186:189], v153 offset:2048
	ds_read_b128 v[190:193], v153 offset:3072
	ds_read_b128 v[194:197], v153 offset:4096
	ds_read_b128 v[198:201], v153 offset:5120
	ds_read_b128 v[202:205], v153 offset:6144
	ds_read_b128 v[206:209], v153 offset:7168
	s_cmp_eq_i32 s10, -2
	s_cbranch_scc1 .Lin_g0_first
.Lin_g0_norm:
	s_add_i32 m0, s38, 0xc000
	s_add_i32 vcc_lo, s97, 0x10000000
	s_add_u32 vcc_lo, s100, vcc_lo
	s_addc_u32 vcc_hi, s101, 0
	global_load_lds_dwordx4 v148, vcc
	s_add_i32 m0, s38, 0xe000
	s_nop 0
	global_load_lds_dwordx4 v150, vcc
	s_waitcnt vmcnt(8)
.Lin_g0_join:
	s_waitcnt lgkmcnt(0)
	s_barrier
	s_setprio 1
	s_waitcnt lgkmcnt(0)
	v_mfma_f32_16x16x32_bf16 v[126:129], v[138:141], v[178:181], v[126:129]
	v_mfma_f32_16x16x32_bf16 v[122:125], v[154:157], v[178:181], v[122:125]
	v_mfma_f32_16x16x32_bf16 v[110:113], v[138:141], v[186:189], v[110:113]
	v_mfma_f32_16x16x32_bf16 v[106:109], v[154:157], v[186:189], v[106:109]
	v_mfma_f32_16x16x32_bf16 v[94:97], v[138:141], v[194:197], v[94:97]
	v_mfma_f32_16x16x32_bf16 v[90:93], v[154:157], v[194:197], v[90:93]
	v_mfma_f32_16x16x32_bf16 v[78:81], v[138:141], v[202:205], v[78:81]
	v_mfma_f32_16x16x32_bf16 v[74:77], v[154:157], v[202:205], v[74:77]
	v_mfma_f32_16x16x32_bf16 v[126:129], v[142:145], v[182:185], v[126:129]
	v_mfma_f32_16x16x32_bf16 v[122:125], v[158:161], v[182:185], v[122:125]
	v_mfma_f32_16x16x32_bf16 v[110:113], v[142:145], v[190:193], v[110:113]
	v_mfma_f32_16x16x32_bf16 v[106:109], v[158:161], v[190:193], v[106:109]
	v_mfma_f32_16x16x32_bf16 v[94:97], v[142:145], v[198:201], v[94:97]
	v_mfma_f32_16x16x32_bf16 v[90:93], v[158:161], v[198:201], v[90:93]
	v_mfma_f32_16x16x32_bf16 v[78:81], v[142:145], v[206:209], v[78:81]
	v_mfma_f32_16x16x32_bf16 v[74:77], v[158:161], v[206:209], v[74:77]
	s_setprio 0
	s_setprio 1
	v_mfma_f32_16x16x32_bf16 v[118:121], v[162:165], v[178:181], v[118:121]
	v_mfma_f32_16x16x32_bf16 v[114:117], v[170:173], v[178:181], v[114:117]
	v_mfma_f32_16x16x32_bf16 v[102:105], v[162:165], v[186:189], v[102:105]
	v_mfma_f32_16x16x32_bf16 v[98:101], v[170:173], v[186:189], v[98:101]
	v_mfma_f32_16x16x32_bf16 v[86:89], v[162:165], v[194:197], v[86:89]
	v_mfma_f32_16x16x32_bf16 v[82:85], v[170:173], v[194:197], v[82:85]
	v_mfma_f32_16x16x32_bf16 v[70:73], v[162:165], v[202:205], v[70:73]
	v_mfma_f32_16x16x32_bf16 v[66:69], v[170:173], v[202:205], v[66:69]
	v_mfma_f32_16x16x32_bf16 v[118:121], v[166:169], v[182:185], v[118:121]
	v_mfma_f32_16x16x32_bf16 v[114:117], v[174:177], v[182:185], v[114:117]
	v_mfma_f32_16x16x32_bf16 v[102:105], v[166:169], v[190:193], v[102:105]
	v_mfma_f32_16x16x32_bf16 v[98:101], v[174:177], v[190:193], v[98:101]
	v_mfma_f32_16x16x32_bf16 v[86:89], v[166:169], v[198:201], v[86:89]
	v_mfma_f32_16x16x32_bf16 v[82:85], v[174:177], v[198:201], v[82:85]
	v_mfma_f32_16x16x32_bf16 v[70:73], v[166:169], v[206:209], v[70:73]
	v_mfma_f32_16x16x32_bf16 v[66:69], v[174:177], v[206:209], v[66:69]
	s_setprio 0
	s_barrier
	s_mov_b32 s97, s82
	ds_read_b128 v[178:181], v153 offset:16384
	ds_read_b128 v[182:185], v153 offset:17408
	ds_read_b128 v[186:189], v153 offset:18432
	ds_read_b128 v[190:193], v153 offset:19456
	ds_read_b128 v[194:197], v153 offset:20480
	ds_read_b128 v[198:201], v153 offset:21504
	ds_read_b128 v[202:205], v153 offset:22528
	ds_read_b128 v[206:209], v153 offset:23552
	s_add_i32 s84, s84, s7
	s_add_i32 vcc_lo, s97, 0x10000000
	s_add_u32 vcc_lo, s100, vcc_lo
	s_addc_u32 vcc_hi, s101, 0
	s_mov_b32 m0, s84
	s_nop 0
	global_load_lds_dwordx4 v149, vcc
	s_add_i32 m0, s84, 0x2000
	s_add_i32 s84, s82, 0x100000
	global_load_lds_dwordx4 v151, vcc
	s_add_i32 s96, s96, s7
	s_add_i32 vcc_lo, s84, 0x10000000
	s_add_u32 vcc_lo, s100, vcc_lo
	s_addc_u32 vcc_hi, s101, 0
	s_mov_b32 m0, s96
	s_nop 0
	global_load_lds_dwordx4 v149, vcc
	s_add_i32 m0, s96, 0x2000
	s_mov_b32 s84, s83
	global_load_lds_dwordx4 v151, vcc
	s_mov_b32 m0, s38
	s_add_i32 vcc_lo, s84, 0x10000000
	s_add_u32 vcc_lo, s100, vcc_lo
	s_addc_u32 vcc_hi, s101, 0
	global_load_lds_dwordx4 v148, vcc
	s_mov_b32 m0, s39
	s_nop 0
	global_load_lds_dwordx4 v150, vcc
	s_cmp_eq_i32 s10, -2
	s_cbranch_scc1 .Lin_g1_first

; #define PG8_STAGE(bufoff, gbase, voff) do { unsigned _g = (gbase); asm volatile("" : "+s"(_g));   _Pragma("unroll") for (int _i = 0; _i < 2; ++_i) \
;         __builtin_amdgcn_global_load_lds((const unsigned*)(wsb + (size_t)(unsigned)(_g + (voff)[_i])), (LAS unsigned*)(lds + (bufoff) + ldsw + _i * 8192), 16, 0, 0); } while (0)
; #define PG8_WAIT_V(n) asm volatile("s_waitcnt vmcnt(" #n ")" ::: "memory")
; #define PG8_WAIT_L(n) asm volatile("s_waitcnt lgkmcnt(" #n ")" ::: "memory")
; #define PG8_BAR __builtin_amdgcn_s_barrier()
; #define PG8_SCHED __builtin_amdgcn_sched_barrier(0)
;     ...
;             PG8_WAIT_V(8); PG8_WAIT_L(0); PG8_BAR; PG8_MMA(1, 0, At, B0); PG8_MMA(1, 1, At, B1); PG8_BAR; PG8_SCHED;
;             PG8_LDB(B0, 1, 0); PG8_LDB(B1, 1, 1); PG8_SCHED; PG8_LDA(At, 1, 0); PG8_STAGE(PG8_SA(0, 1), a2 + hstep, voffA);
.Lin_g1_join:
	s_waitcnt lgkmcnt(0)
	s_barrier
	s_setprio 1
	s_waitcnt lgkmcnt(0)
	v_mfma_f32_16x16x32_bf16 v[62:65], v[138:141], v[178:181], v[62:65]
	v_mfma_f32_16x16x32_bf16 v[58:61], v[154:157], v[178:181], v[58:61]
	v_mfma_f32_16x16x32_bf16 v[46:49], v[138:141], v[186:189], v[46:49]
	v_mfma_f32_16x16x32_bf16 v[42:45], v[154:157], v[186:189], v[42:45]
	v_mfma_f32_16x16x32_bf16 v[30:33], v[138:141], v[194:197], v[30:33]
	v_mfma_f32_16x16x32_bf16 v[26:29], v[154:157], v[194:197], v[26:29]
	v_mfma_f32_16x16x32_bf16 v[14:17], v[138:141], v[202:205], v[14:17]
	v_mfma_f32_16x16x32_bf16 v[10:13], v[154:157], v[202:205], v[10:13]
	v_mfma_f32_16x16x32_bf16 v[62:65], v[142:145], v[182:185], v[62:65]
	v_mfma_f32_16x16x32_bf16 v[58:61], v[158:161], v[182:185], v[58:61]
	v_mfma_f32_16x16x32_bf16 v[46:49], v[142:145], v[190:193], v[46:49]
	v_mfma_f32_16x16x32_bf16 v[42:45], v[158:161], v[190:193], v[42:45]
	v_mfma_f32_16x16x32_bf16 v[30:33], v[142:145], v[198:201], v[30:33]
	v_mfma_f32_16x16x32_bf16 v[26:29], v[158:161], v[198:201], v[26:29]
	v_mfma_f32_16x16x32_bf16 v[14:17], v[142:145], v[206:209], v[14:17]
	v_mfma_f32_16x16x32_bf16 v[10:13], v[158:161], v[206:209], v[10:13]
	s_setprio 0
	s_setprio 1
	v_mfma_f32_16x16x32_bf16 v[54:57], v[162:165], v[178:181], v[54:57]
	v_mfma_f32_16x16x32_bf16 v[50:53], v[170:173], v[178:181], v[50:53]
	v_mfma_f32_16x16x32_bf16 v[38:41], v[162:165], v[186:189], v[38:41]
	v_mfma_f32_16x16x32_bf16 v[34:37], v[170:173], v[186:189], v[34:37]
	v_mfma_f32_16x16x32_bf16 v[22:25], v[162:165], v[194:197], v[22:25]
	v_mfma_f32_16x16x32_bf16 v[18:21], v[170:173], v[194:197], v[18:21]
	v_mfma_f32_16x16x32_bf16 v[6:9], v[162:165], v[202:205], v[6:9]
	v_mfma_f32_16x16x32_bf16 v[2:5], v[170:173], v[202:205], v[2:5]
	v_mfma_f32_16x16x32_bf16 v[54:57], v[166:169], v[182:185], v[54:57]
	v_mfma_f32_16x16x32_bf16 v[50:53], v[174:177], v[182:185], v[50:53]
	v_mfma_f32_16x16x32_bf16 v[38:41], v[166:169], v[190:193], v[38:41]
	v_mfma_f32_16x16x32_bf16 v[34:37], v[174:177], v[190:193], v[34:37]
	v_mfma_f32_16x16x32_bf16 v[22:25], v[166:169], v[198:201], v[22:25]
	v_mfma_f32_16x16x32_bf16 v[18:21], v[174:177], v[198:201], v[18:21]
	v_mfma_f32_16x16x32_bf16 v[6:9], v[166:169], v[206:209], v[6:9]
	v_mfma_f32_16x16x32_bf16 v[2:5], v[174:177], v[206:209], v[2:5]
	s_setprio 0
	s_barrier
	s_add_i32 s84, 0, 0x18000
	v_add_u32_e32 v0, s84, v152
	s_add_i32 s96, 0, 0x1c000
	ds_read_b128 v[138:141], v0
	ds_read_b128 v[142:145], v0 offset:1024
	ds_read_b128 v[154:157], v0 offset:2048
	ds_read_b128 v[158:161], v0 offset:3072
	v_add_u32_e32 v0, s96, v152
	ds_read_b128 v[162:165], v0
	ds_read_b128 v[166:169], v0 offset:1024
	ds_read_b128 v[170:173], v0 offset:2048
	ds_read_b128 v[174:177], v0 offset:3072
	s_add_i32 s83, s83, 0x100000
	ds_read_b128 v[178:181], v153 offset:32768
	ds_read_b128 v[182:185], v153 offset:33792
	ds_read_b128 v[186:189], v153 offset:34816
	ds_read_b128 v[190:193], v153 offset:35840
	ds_read_b128 v[194:197], v153 offset:36864
	ds_read_b128 v[198:201], v153 offset:37888
	ds_read_b128 v[202:205], v153 offset:38912
	ds_read_b128 v[206:209], v153 offset:39936
	s_mov_b32 m0, s44
	s_add_i32 vcc_lo, s83, 0x10000000
	s_add_u32 vcc_lo, s100, vcc_lo
	s_addc_u32 vcc_hi, s101, 0
	global_load_lds_dwordx4 v148, vcc
	s_mov_b32 m0, s45
	s_nop 0
	global_load_lds_dwordx4 v150, vcc
	s_cmp_eq_i32 s10, -2
	s_cbranch_scc1 .Lin_g2_first

; #define PG8_STAGE(bufoff, gbase, voff) do { unsigned _g = (gbase); asm volatile("" : "+s"(_g));   _Pragma("unroll") for (int _i = 0; _i < 2; ++_i) \
;         __builtin_amdgcn_global_load_lds((const unsigned*)(wsb + (size_t)(unsigned)(_g + (voff)[_i])), (LAS unsigned*)(lds + (bufoff) + ldsw + _i * 8192), 16, 0, 0); } while (0)
; #define PG8_WAIT_V(n) asm volatile("s_waitcnt vmcnt(" #n ")" ::: "memory")
; #define PG8_WAIT_L(n) asm volatile("s_waitcnt lgkmcnt(" #n ")" ::: "memory")
; #define PG8_BAR __builtin_amdgcn_s_barrier()
; #define PG8_SCHED __builtin_amdgcn_sched_barrier(0)
;     ...
;             PG8_WAIT_V(8); PG8_WAIT_L(0); PG8_BAR; PG8_MMA(0, 0, At, B0); PG8_MMA(0, 1, At, B1); PG8_BAR; PG8_SCHED;
;             PG8_LDA(At, 1, 1); PG8_STAGE(PG8_SB(1, 0), b3, voffB); PG8_STAGE(PG8_SB(1, 1), b3 + hstep, voffB); PG8_STAGE(PG8_SA(1, 0), a3, voffA);
;             PG8_WAIT_V(8); PG8_WAIT_L(0); PG8_BAR; PG8_MMA(1, 0, At, B0); PG8_MMA(1, 1, At, B1); PG8_BAR; PG8_SCHED;
.Lin_g2_join:
	s_waitcnt lgkmcnt(0)
	s_barrier
	s_setprio 1
	s_waitcnt lgkmcnt(0)
	v_mfma_f32_16x16x32_bf16 v[126:129], v[138:141], v[178:181], v[126:129]
	v_mfma_f32_16x16x32_bf16 v[122:125], v[154:157], v[178:181], v[122:125]
	v_mfma_f32_16x16x32_bf16 v[110:113], v[138:141], v[186:189], v[110:113]
	v_mfma_f32_16x16x32_bf16 v[106:109], v[154:157], v[186:189], v[106:109]
	v_mfma_f32_16x16x32_bf16 v[94:97], v[138:141], v[194:197], v[94:97]
	v_mfma_f32_16x16x32_bf16 v[90:93], v[154:157], v[194:197], v[90:93]
	v_mfma_f32_16x16x32_bf16 v[78:81], v[138:141], v[202:205], v[78:81]
	v_mfma_f32_16x16x32_bf16 v[74:77], v[154:157], v[202:205], v[74:77]
	v_mfma_f32_16x16x32_bf16 v[126:129], v[142:145], v[182:185], v[126:129]
	v_mfma_f32_16x16x32_bf16 v[122:125], v[158:161], v[182:185], v[122:125]
	v_mfma_f32_16x16x32_bf16 v[110:113], v[142:145], v[190:193], v[110:113]
	v_mfma_f32_16x16x32_bf16 v[106:109], v[158:161], v[190:193], v[106:109]
	v_mfma_f32_16x16x32_bf16 v[94:97], v[142:145], v[198:201], v[94:97]
	v_mfma_f32_16x16x32_bf16 v[90:93], v[158:161], v[198:201], v[90:93]
	v_mfma_f32_16x16x32_bf16 v[78:81], v[142:145], v[206:209], v[78:81]
	v_mfma_f32_16x16x32_bf16 v[74:77], v[158:161], v[206:209], v[74:77]
	s_setprio 0
	s_setprio 1
	v_mfma_f32_16x16x32_bf16 v[118:121], v[162:165], v[178:181], v[118:121]
	v_mfma_f32_16x16x32_bf16 v[114:117], v[170:173], v[178:181], v[114:117]
	v_mfma_f32_16x16x32_bf16 v[102:105], v[162:165], v[186:189], v[102:105]
	v_mfma_f32_16x16x32_bf16 v[98:101], v[170:173], v[186:189], v[98:101]
	v_mfma_f32_16x16x32_bf16 v[86:89], v[162:165], v[194:197], v[86:89]
	v_mfma_f32_16x16x32_bf16 v[82:85], v[170:173], v[194:197], v[82:85]
	v_mfma_f32_16x16x32_bf16 v[70:73], v[162:165], v[202:205], v[70:73]
	v_mfma_f32_16x16x32_bf16 v[66:69], v[170:173], v[202:205], v[66:69]
	v_mfma_f32_16x16x32_bf16 v[118:121], v[166:169], v[182:185], v[118:121]
	v_mfma_f32_16x16x32_bf16 v[114:117], v[174:177], v[182:185], v[114:117]
	v_mfma_f32_16x16x32_bf16 v[102:105], v[166:169], v[190:193], v[102:105]
	v_mfma_f32_16x16x32_bf16 v[98:101], v[174:177], v[190:193], v[98:101]
	v_mfma_f32_16x16x32_bf16 v[86:89], v[166:169], v[198:201], v[86:89]
	v_mfma_f32_16x16x32_bf16 v[82:85], v[174:177], v[198:201], v[82:85]
	v_mfma_f32_16x16x32_bf16 v[70:73], v[166:169], v[206:209], v[70:73]
	v_mfma_f32_16x16x32_bf16 v[66:69], v[174:177], v[206:209], v[66:69]
	s_setprio 0
	s_barrier
	s_add_i32 s83, s82, 0x80
	ds_read_b128 v[178:181], v153 offset:49152
	ds_read_b128 v[182:185], v153 offset:50176
	ds_read_b128 v[186:189], v153 offset:51200
	ds_read_b128 v[190:193], v153 offset:52224
	ds_read_b128 v[194:197], v153 offset:53248
	ds_read_b128 v[198:201], v153 offset:54272
	ds_read_b128 v[202:205], v153 offset:55296
	ds_read_b128 v[206:209], v153 offset:56320
	s_add_i32 s84, s84, s7
	s_add_i32 vcc_lo, s83, 0x10000000
	s_add_u32 vcc_lo, s100, vcc_lo
	s_addc_u32 vcc_hi, s101, 0
	s_mov_b32 m0, s84
	s_nop 0
	global_load_lds_dwordx4 v149, vcc
	s_add_i32 m0, s84, 0x2000
	s_add_i32 s82, s82, 0x100080
	global_load_lds_dwordx4 v151, vcc
	s_add_i32 s83, s96, s7
	s_add_i32 vcc_lo, s82, 0x10000000
	s_add_u32 vcc_lo, s100, vcc_lo
	s_addc_u32 vcc_hi, s101, 0
	s_mov_b32 m0, s83
	s_nop 0
	global_load_lds_dwordx4 v149, vcc
	s_add_i32 m0, s83, 0x2000
	s_nop 0
	global_load_lds_dwordx4 v151, vcc
	s_mov_b32 m0, s46
	s_add_i32 vcc_lo, s11, 0x10000000
	s_add_u32 vcc_lo, s100, vcc_lo
	s_addc_u32 vcc_hi, s101, 0
	global_load_lds_dwordx4 v148, vcc
	s_mov_b32 m0, s47
	s_nop 0
	global_load_lds_dwordx4 v150, vcc
	s_waitcnt vmcnt(8)
	s_waitcnt lgkmcnt(0)
	s_barrier
	s_setprio 1
	s_waitcnt lgkmcnt(0)
	v_mfma_f32_16x16x32_bf16 v[62:65], v[138:141], v[178:181], v[62:65]
	v_mfma_f32_16x16x32_bf16 v[58:61], v[154:157], v[178:181], v[58:61]
	v_mfma_f32_16x16x32_bf16 v[46:49], v[138:141], v[186:189], v[46:49]
	v_mfma_f32_16x16x32_bf16 v[42:45], v[154:157], v[186:189], v[42:45]
	v_mfma_f32_16x16x32_bf16 v[30:33], v[138:141], v[194:197], v[30:33]
	v_mfma_f32_16x16x32_bf16 v[26:29], v[154:157], v[194:197], v[26:29]
	v_mfma_f32_16x16x32_bf16 v[14:17], v[138:141], v[202:205], v[14:17]
	v_mfma_f32_16x16x32_bf16 v[10:13], v[154:157], v[202:205], v[10:13]
	v_mfma_f32_16x16x32_bf16 v[62:65], v[142:145], v[182:185], v[62:65]
	v_mfma_f32_16x16x32_bf16 v[58:61], v[158:161], v[182:185], v[58:61]
	v_mfma_f32_16x16x32_bf16 v[46:49], v[142:145], v[190:193], v[46:49]
	v_mfma_f32_16x16x32_bf16 v[42:45], v[158:161], v[190:193], v[42:45]
	v_mfma_f32_16x16x32_bf16 v[30:33], v[142:145], v[198:201], v[30:33]
	v_mfma_f32_16x16x32_bf16 v[26:29], v[158:161], v[198:201], v[26:29]
	v_mfma_f32_16x16x32_bf16 v[14:17], v[142:145], v[206:209], v[14:17]
	v_mfma_f32_16x16x32_bf16 v[10:13], v[158:161], v[206:209], v[10:13]
	s_setprio 0
	s_setprio 1
	v_mfma_f32_16x16x32_bf16 v[54:57], v[162:165], v[178:181], v[54:57]
	v_mfma_f32_16x16x32_bf16 v[50:53], v[170:173], v[178:181], v[50:53]
	v_mfma_f32_16x16x32_bf16 v[38:41], v[162:165], v[186:189], v[38:41]
	v_mfma_f32_16x16x32_bf16 v[34:37], v[170:173], v[186:189], v[34:37]
	v_mfma_f32_16x16x32_bf16 v[22:25], v[162:165], v[194:197], v[22:25]
	v_mfma_f32_16x16x32_bf16 v[18:21], v[170:173], v[194:197], v[18:21]
	v_mfma_f32_16x16x32_bf16 v[6:9], v[162:165], v[202:205], v[6:9]
	v_mfma_f32_16x16x32_bf16 v[2:5], v[170:173], v[202:205], v[2:5]
	v_mfma_f32_16x16x32_bf16 v[54:57], v[166:169], v[182:185], v[54:57]
	v_mfma_f32_16x16x32_bf16 v[50:53], v[174:177], v[182:185], v[50:53]
	v_mfma_f32_16x16x32_bf16 v[38:41], v[166:169], v[190:193], v[38:41]
	v_mfma_f32_16x16x32_bf16 v[34:37], v[174:177], v[190:193], v[34:37]
	v_mfma_f32_16x16x32_bf16 v[22:25], v[166:169], v[198:201], v[22:25]
	v_mfma_f32_16x16x32_bf16 v[18:21], v[174:177], v[198:201], v[18:21]
	v_mfma_f32_16x16x32_bf16 v[6:9], v[166:169], v[206:209], v[6:9]
	v_mfma_f32_16x16x32_bf16 v[2:5], v[174:177], v[206:209], v[2:5]
	s_setprio 0
	s_barrier
	s_add_i32 s10, s10, 2
	s_addk_i32 s8, 0x100
	s_addk_i32 s9, 0x100
	s_cmp_gt_u32 s10, 61
	s_cbranch_scc0 .LBB0_279
	s_mov_b64 s[10:11], -1
	s_mov_b64 s[4:5], 0
	s_cmp_lt_i32 s18, 1
	s_mov_b64 s[8:9], 0
	v_mbcnt_lo_u32_b32 v0, -1, 0
	v_mbcnt_hi_u32_b32 v0, -1, v0
	s_cbranch_scc1 .LBB0_295
	s_cmp_lg_u32 s18, 1
	s_cselect_b64 s[8:9], -1, 0
	s_cbranch_execz .LBB0_296

; #define PG8_STAGE(bufoff, gbase, voff) do { unsigned _g = (gbase); asm volatile("" : "+s"(_g));   _Pragma("unroll") for (int _i = 0; _i < 2; ++_i) \
;         __builtin_amdgcn_global_load_lds((const unsigned*)(wsb + (size_t)(unsigned)(_g + (voff)[_i])), (LAS unsigned*)(lds + (bufoff) + ldsw + _i * 8192), 16, 0, 0); } while (0)
; #define PG8_WAIT_V(n) asm volatile("s_waitcnt vmcnt(" #n ")" ::: "memory")
; #define PG8_WAIT_L(n) asm volatile("s_waitcnt lgkmcnt(" #n ")" ::: "memory")
; #define PG8_BAR __builtin_amdgcn_s_barrier()
; #define PG8_SCHED __builtin_amdgcn_sched_barrier(0)
;     ...
;             const unsigned a1 = cA + (unsigned)(t + 1) * kstep;
;             const unsigned a2 = last ? nA : cA + (unsigned)(t + 2) * kstep, b2 = last ? nB : cB + (unsigned)(t + 2) * kstep;
;             const unsigned a3 = a2 + kstep, b3 = b2 + kstep;
;             if constexpr (SP2) {
;             PG8_LDB(B0, 0, 0); PG8_LDB(B1, 0, 1); PG8_SCHED; PG8_LDA(At, 0, 0); PG8_STAGE(PG8_SA(1, 1), a1 + hstep, voffA);
;             PG8_WAIT_V(8); PG8_WAIT_L(0); PG8_BAR; PG8_MMA(0, 0, At, B0); PG8_MMA(0, 1, At, B1); PG8_BAR; PG8_SCHED;
;             PG8_LDA(At, 0, 1); PG8_STAGE(PG8_SB(0, 0), b2, voffB); PG8_STAGE(PG8_SB(0, 1), b2 + hstep, voffB); PG8_STAGE(PG8_SA(0, 0), a2, voffA);
;             PG8_WAIT_V(8); PG8_WAIT_L(0); PG8_BAR; PG8_MMA(1, 0, At, B0); PG8_MMA(1, 1, At, B1); PG8_BAR; PG8_SCHED;
;             PG8_LDB(B0, 1, 0); PG8_LDB(B1, 1, 1); PG8_SCHED; PG8_LDA(At, 1, 0); PG8_STAGE(PG8_SA(0, 1), a2 + hstep, voffA);
;             PG8_WAIT_V(8); PG8_WAIT_L(0); PG8_BAR; PG8_MMA(0, 0, At, B0); PG8_MMA(0, 1, At, B1); PG8_BAR; PG8_SCHED;
.LBB0_559:
	v_readfirstlane_b32 s100, v130
	v_readfirstlane_b32 s101, v131
	s_nop 1
	s_sub_u32 s100, s100, 0x10000000
	s_subb_u32 s101, s101, 0
	s_add_i32 s47, s44, 0xfff80080
	s_cmp_eq_u32 s46, 28
	s_cselect_b32 s83, s36, s47
	s_cselect_b32 s47, s37, s45
	s_add_i32 s84, 0, 0x10000
	v_add_u32_e32 v0, s84, v138
	s_add_i32 s86, 0, 0x14000
	ds_read_b128 v[140:143], v0
	ds_read_b128 v[144:147], v0 offset:1024
	ds_read_b128 v[148:151], v0 offset:2048
	ds_read_b128 v[152:155], v0 offset:3072
	v_add_u32_e32 v0, s86, v138
	ds_read_b128 v[156:159], v0
	ds_read_b128 v[160:163], v0 offset:1024
	ds_read_b128 v[164:167], v0 offset:2048
	ds_read_b128 v[168:171], v0 offset:3072
	s_add_i32 s82, s83, 0x80
	s_mov_b32 s87, s44
	ds_read_b128 v[172:175], v139
	ds_read_b128 v[176:179], v139 offset:1024
	ds_read_b128 v[180:183], v139 offset:2048
	ds_read_b128 v[184:187], v139 offset:3072
	ds_read_b128 v[188:191], v139 offset:4096
	ds_read_b128 v[192:195], v139 offset:5120
	ds_read_b128 v[196:199], v139 offset:6144
	ds_read_b128 v[200:203], v139 offset:7168
	s_add_i32 m0, s9, 0xc000
	s_add_i32 vcc_lo, s87, 0x10000000
	s_add_u32 vcc_lo, s100, vcc_lo
	s_addc_u32 vcc_hi, s101, 0
	global_load_lds_dwordx4 v134, vcc
	s_add_i32 m0, s9, 0xe000
	s_nop 0
	global_load_lds_dwordx4 v136, vcc
	s_waitcnt vmcnt(8)
	s_waitcnt lgkmcnt(0)
	s_barrier
	s_setprio 1
	s_waitcnt lgkmcnt(0)
	v_mfma_f32_16x16x128_f8f6f4 v[126:129], v[140:147], v[172:179], v[126:129]
	v_mfma_f32_16x16x128_f8f6f4 v[122:125], v[148:155], v[172:179], v[122:125]
	v_mfma_f32_16x16x128_f8f6f4 v[110:113], v[140:147], v[180:187], v[110:113]
	v_mfma_f32_16x16x128_f8f6f4 v[106:109], v[148:155], v[180:187], v[106:109]
	v_mfma_f32_16x16x128_f8f6f4 v[204:207], v[140:147], v[188:195], v[94:97]
	v_mfma_f32_16x16x128_f8f6f4 v[208:211], v[148:155], v[188:195], v[90:93]
	v_mfma_f32_16x16x128_f8f6f4 v[212:215], v[140:147], v[196:203], v[78:81]
	v_mfma_f32_16x16x128_f8f6f4 v[216:219], v[148:155], v[196:203], v[74:77]
	s_setprio 0
	s_setprio 1
	v_mfma_f32_16x16x128_f8f6f4 v[118:121], v[156:163], v[172:179], v[118:121]
	v_mfma_f32_16x16x128_f8f6f4 v[114:117], v[164:171], v[172:179], v[114:117]
	v_mfma_f32_16x16x128_f8f6f4 v[102:105], v[156:163], v[180:187], v[102:105]
	v_mfma_f32_16x16x128_f8f6f4 v[98:101], v[164:171], v[180:187], v[98:101]
	v_mfma_f32_16x16x128_f8f6f4 v[172:175], v[156:163], v[188:195], v[86:89]
	v_mfma_f32_16x16x128_f8f6f4 v[176:179], v[164:171], v[188:195], v[82:85]
	v_mfma_f32_16x16x128_f8f6f4 v[180:183], v[156:163], v[196:203], v[70:73]
	v_mfma_f32_16x16x128_f8f6f4 v[184:187], v[164:171], v[196:203], v[66:69]
	s_setprio 0
	s_barrier
	s_mov_b32 s87, s47
	s_nop 3
	ds_read_b128 v[66:69], v139 offset:16384
	ds_read_b128 v[70:73], v139 offset:17408
	ds_read_b128 v[74:77], v139 offset:18432
	ds_read_b128 v[78:81], v139 offset:19456
	ds_read_b128 v[82:85], v139 offset:20480
	ds_read_b128 v[86:89], v139 offset:21504
	ds_read_b128 v[90:93], v139 offset:22528
	ds_read_b128 v[94:97], v139 offset:23552
	s_add_i32 s84, s84, s7
	s_add_i32 vcc_lo, s87, 0x10000000
	s_add_u32 vcc_lo, s100, vcc_lo
	s_addc_u32 vcc_hi, s101, 0
	s_mov_b32 m0, s84
	s_nop 0
	global_load_lds_dwordx4 v135, vcc
	s_add_i32 m0, s84, 0x2000
	s_add_i32 s84, s47, 0x80000
	global_load_lds_dwordx4 v137, vcc
	s_add_i32 s86, s86, s7
	s_add_i32 vcc_lo, s84, 0x10000000
	s_add_u32 vcc_lo, s100, vcc_lo
	s_addc_u32 vcc_hi, s101, 0
	s_mov_b32 m0, s86
	s_nop 0
	global_load_lds_dwordx4 v135, vcc
	s_add_i32 m0, s86, 0x2000
	s_mov_b32 s84, s83
	global_load_lds_dwordx4 v137, vcc
	s_mov_b32 m0, s9
	s_add_i32 vcc_lo, s84, 0x10000000
	s_add_u32 vcc_lo, s100, vcc_lo
	s_addc_u32 vcc_hi, s101, 0
	global_load_lds_dwordx4 v134, vcc
	s_mov_b32 m0, s11
	s_nop 0
	global_load_lds_dwordx4 v136, vcc
	s_waitcnt vmcnt(8)
	s_waitcnt lgkmcnt(0)
	s_barrier
	s_setprio 1
	s_waitcnt lgkmcnt(0)
	v_mfma_f32_16x16x128_f8f6f4 v[62:65], v[140:147], v[66:73], v[62:65]
	v_mfma_f32_16x16x128_f8f6f4 v[58:61], v[148:155], v[66:73], v[58:61]
	v_mfma_f32_16x16x128_f8f6f4 v[188:191], v[140:147], v[74:81], v[46:49]
	v_mfma_f32_16x16x128_f8f6f4 v[192:195], v[148:155], v[74:81], v[42:45]
	v_mfma_f32_16x16x128_f8f6f4 v[196:199], v[140:147], v[82:89], v[30:33]
	v_mfma_f32_16x16x128_f8f6f4 v[200:203], v[148:155], v[82:89], v[26:29]
	v_mfma_f32_16x16x128_f8f6f4 v[220:223], v[140:147], v[90:97], v[14:17]
	v_mfma_f32_16x16x128_f8f6f4 v[224:227], v[148:155], v[90:97], v[10:13]
	s_setprio 0
	s_setprio 1
	v_mfma_f32_16x16x128_f8f6f4 v[54:57], v[156:163], v[66:73], v[54:57]
	v_mfma_f32_16x16x128_f8f6f4 v[50:53], v[164:171], v[66:73], v[50:53]
	v_mfma_f32_16x16x128_f8f6f4 v[228:231], v[156:163], v[74:81], v[38:41]
	v_mfma_f32_16x16x128_f8f6f4 v[232:235], v[164:171], v[74:81], v[34:37]
	v_mfma_f32_16x16x128_f8f6f4 v[236:239], v[156:163], v[82:89], v[22:25]
	v_mfma_f32_16x16x128_f8f6f4 v[246:249], v[164:171], v[82:89], v[18:21]
	v_mfma_f32_16x16x128_f8f6f4 v[250:253], v[156:163], v[90:97], v[6:9]
	v_mfma_f32_16x16x128_f8f6f4 v[240:243], v[164:171], v[90:97], v[2:5]
	s_setprio 0
	s_barrier
	s_add_i32 s84, 0, 0x18000
	v_add_u32_e32 v0, s84, v138
	s_add_i32 s86, 0, 0x1c000
	s_nop 1
	ds_read_b128 v[2:5], v0
	ds_read_b128 v[6:9], v0 offset:1024
	ds_read_b128 v[18:21], v0 offset:2048
	ds_read_b128 v[22:25], v0 offset:3072
	v_add_u32_e32 v0, s86, v138
	ds_read_b128 v[140:143], v0
	ds_read_b128 v[144:147], v0 offset:1024
	ds_read_b128 v[148:151], v0 offset:2048
	ds_read_b128 v[152:155], v0 offset:3072
	s_add_i32 s83, s83, 0x80000
	ds_read_b128 v[10:13], v139 offset:32768
	ds_read_b128 v[14:17], v139 offset:33792
	ds_read_b128 v[26:29], v139 offset:34816
	ds_read_b128 v[30:33], v139 offset:35840
	ds_read_b128 v[34:37], v139 offset:36864
	ds_read_b128 v[38:41], v139 offset:37888
	ds_read_b128 v[42:45], v139 offset:38912
	ds_read_b128 v[46:49], v139 offset:39936
	s_mov_b32 m0, s12
	s_add_i32 vcc_lo, s83, 0x10000000
	s_add_u32 vcc_lo, s100, vcc_lo
	s_addc_u32 vcc_hi, s101, 0
	global_load_lds_dwordx4 v134, vcc
	s_mov_b32 m0, s13
	s_nop 0
	global_load_lds_dwordx4 v136, vcc
	s_waitcnt vmcnt(8)
	s_waitcnt lgkmcnt(0)
	s_barrier
; #define GAS __attribute__((address_space(1)))
; __device__ __forceinline__ unsigned gate_pk4(const f32x4& g) { return gate_q8(g[0]) | (gate_q8(g[1]) << 8) | (gate_q8(g[2]) << 16) | (gate_q8(g[3]) << 24); }
; #define PG8_STAGE(bufoff, gbase, voff) do { unsigned _g = (gbase); asm volatile("" : "+s"(_g));   _Pragma("unroll") for (int _i = 0; _i < 2; ++_i) \
;         __builtin_amdgcn_global_load_lds((const unsigned*)(wsb + (size_t)(unsigned)(_g + (voff)[_i])), (LAS unsigned*)(lds + (bufoff) + ldsw + _i * 8192), 16, 0, 0); } while (0)
; #define PG8_WAIT_V(n) asm volatile("s_waitcnt vmcnt(" #n ")" ::: "memory")
; #define PG8_WAIT_L(n) asm volatile("s_waitcnt lgkmcnt(" #n ")" ::: "memory")
; #define PG8_BAR __builtin_amdgcn_s_barrier()
; #define PG8_SCHED __builtin_amdgcn_sched_barrier(0)
;     ...
;             PG8_WAIT_V(8); PG8_WAIT_L(0); PG8_BAR; PG8_MMA(0, 0, At, B0); PG8_MMA(0, 1, At, B1); PG8_BAR; PG8_SCHED;
;             PG8_LDA(At, 1, 1); PG8_STAGE(PG8_SB(1, 0), b3, voffB); PG8_STAGE(PG8_SB(1, 1), b3 + hstep, voffB); PG8_STAGE(PG8_SA(1, 0), a3, voffA);
;             PG8_WAIT_V(8); PG8_WAIT_L(0); PG8_BAR; PG8_MMA(1, 0, At, B0); PG8_MMA(1, 1, At, B1); PG8_BAR; PG8_SCHED;
;     __device__ __forceinline__ void operator()(const f32x4 (&acc)[2][2][4][2], const pg8::GUnit& u, int wr, int wc, int fr, int fq) const {
;     ...
;         GAS unsigned char* gb = (GAS unsigned char*)P + (size_t)(u.pm * 256 + (wr * 4 + wc) * 32 + fq) * (INW * 2) + (GA * 2 + u.pn * 256 + fr * 16);
; #pragma unroll
;         for (int ai = 0; ai < 2; ++ai)
; #pragma unroll
;             for (int m = 0; m < 4; ++m) { u32x4 w; unsigned wq[4];
; #pragma unroll
;                 for (int bj = 0; bj < 2; ++bj)
; #pragma unroll
;                     for (int n = 0; n < 2; ++n) { f32x4 v = acc[ai][bj][m][n];
; #pragma unroll
;                         for (int j = 0; j < 4; ++j) v[j] = __builtin_amdgcn_rcpf(1.0f + __builtin_amdgcn_exp2f(v[j] * (-LOG2E * G8_DESCALE)));
;                         wq[bj * 2 + n] = gate_pk4(v); }
	s_setprio 1
	s_waitcnt lgkmcnt(0)
	v_mfma_f32_16x16x128_f8f6f4 v[126:129], v[2:9], v[10:17], v[126:129]
	v_mfma_f32_16x16x128_f8f6f4 v[122:125], v[18:25], v[10:17], v[122:125]
	v_mfma_f32_16x16x128_f8f6f4 v[110:113], v[2:9], v[26:33], v[110:113]
	v_mfma_f32_16x16x128_f8f6f4 v[106:109], v[18:25], v[26:33], v[106:109]
	v_mfma_f32_16x16x128_f8f6f4 v[94:97], v[2:9], v[34:41], v[204:207]
	v_mfma_f32_16x16x128_f8f6f4 v[90:93], v[18:25], v[34:41], v[208:211]
	v_mfma_f32_16x16x128_f8f6f4 v[78:81], v[2:9], v[42:49], v[212:215]
	v_mfma_f32_16x16x128_f8f6f4 v[74:77], v[18:25], v[42:49], v[216:219]
	s_setprio 0
	s_setprio 1
	v_mfma_f32_16x16x128_f8f6f4 v[118:121], v[140:147], v[10:17], v[118:121]
	v_mfma_f32_16x16x128_f8f6f4 v[114:117], v[148:155], v[10:17], v[114:117]
	v_mfma_f32_16x16x128_f8f6f4 v[102:105], v[140:147], v[26:33], v[102:105]
	v_mfma_f32_16x16x128_f8f6f4 v[98:101], v[148:155], v[26:33], v[98:101]
	v_mfma_f32_16x16x128_f8f6f4 v[86:89], v[140:147], v[34:41], v[172:175]
	v_mfma_f32_16x16x128_f8f6f4 v[82:85], v[148:155], v[34:41], v[176:179]
	v_mfma_f32_16x16x128_f8f6f4 v[70:73], v[140:147], v[42:49], v[180:183]
	v_mfma_f32_16x16x128_f8f6f4 v[66:69], v[148:155], v[42:49], v[184:187]
	s_setprio 0
	s_barrier
	s_add_i32 s83, s47, 0x80
	ds_read_b128 v[34:37], v139 offset:49152
	ds_read_b128 v[38:41], v139 offset:50176
	ds_read_b128 v[156:159], v139 offset:51200
	ds_read_b128 v[160:163], v139 offset:52224
	ds_read_b128 v[164:167], v139 offset:53248
	ds_read_b128 v[168:171], v139 offset:54272
	ds_read_b128 v[172:175], v139 offset:55296
	ds_read_b128 v[176:179], v139 offset:56320
	s_add_i32 s84, s84, s7
	s_add_i32 vcc_lo, s83, 0x10000000
	s_add_u32 vcc_lo, s100, vcc_lo
	s_addc_u32 vcc_hi, s101, 0
	s_mov_b32 m0, s84
	s_nop 0
	global_load_lds_dwordx4 v135, vcc
	s_add_i32 m0, s84, 0x2000
	s_add_i32 s47, s47, 0x80080
	global_load_lds_dwordx4 v137, vcc
	s_add_i32 s83, s86, s7
	s_add_i32 vcc_lo, s47, 0x10000000
	s_add_u32 vcc_lo, s100, vcc_lo
	s_addc_u32 vcc_hi, s101, 0
	s_mov_b32 m0, s83
	s_nop 0
	global_load_lds_dwordx4 v135, vcc
	s_add_i32 m0, s83, 0x2000
	s_nop 0
	global_load_lds_dwordx4 v137, vcc
	s_mov_b32 m0, s18
	s_add_i32 vcc_lo, s82, 0x10000000
	s_add_u32 vcc_lo, s100, vcc_lo
	s_addc_u32 vcc_hi, s101, 0
	global_load_lds_dwordx4 v134, vcc
	s_mov_b32 m0, s22
	s_nop 0
	global_load_lds_dwordx4 v136, vcc
	s_waitcnt vmcnt(8)
	s_waitcnt lgkmcnt(0)
	s_barrier
	s_setprio 1
	s_waitcnt lgkmcnt(0)
	v_mfma_f32_16x16x128_f8f6f4 v[62:65], v[2:9], v[34:41], v[62:65]
	v_mfma_f32_16x16x128_f8f6f4 v[58:61], v[18:25], v[34:41], v[58:61]
	v_mfma_f32_16x16x128_f8f6f4 v[46:49], v[2:9], v[156:163], v[188:191]
	v_mfma_f32_16x16x128_f8f6f4 v[42:45], v[18:25], v[156:163], v[192:195]
	v_mfma_f32_16x16x128_f8f6f4 v[30:33], v[2:9], v[164:171], v[196:199]
	v_mfma_f32_16x16x128_f8f6f4 v[26:29], v[18:25], v[164:171], v[200:203]
	v_mfma_f32_16x16x128_f8f6f4 v[14:17], v[2:9], v[172:179], v[220:223]
	v_mfma_f32_16x16x128_f8f6f4 v[10:13], v[18:25], v[172:179], v[224:227]
	s_setprio 0
	s_setprio 1
	v_mfma_f32_16x16x128_f8f6f4 v[54:57], v[140:147], v[34:41], v[54:57]
	v_mfma_f32_16x16x128_f8f6f4 v[50:53], v[148:155], v[34:41], v[50:53]
	v_mfma_f32_16x16x128_f8f6f4 v[38:41], v[140:147], v[156:163], v[228:231]
	v_mfma_f32_16x16x128_f8f6f4 v[34:37], v[148:155], v[156:163], v[232:235]
	v_mfma_f32_16x16x128_f8f6f4 v[22:25], v[140:147], v[164:171], v[236:239]
	v_mfma_f32_16x16x128_f8f6f4 v[18:21], v[148:155], v[164:171], v[246:249]
	v_mfma_f32_16x16x128_f8f6f4 v[6:9], v[140:147], v[172:179], v[250:253]
	v_mfma_f32_16x16x128_f8f6f4 v[2:5], v[148:155], v[172:179], v[240:243]
	s_setprio 0
	s_barrier
	s_add_i32 s46, s46, 2
	s_addk_i32 s44, 0x100
	s_addk_i32 s45, 0x100
	s_cmp_gt_u32 s46, 29
	s_cbranch_scc0 .LBB0_559
	v_mbcnt_lo_u32_b32 v0, -1, 0
	v_mbcnt_hi_u32_b32 v0, -1, v0
	s_lshl_b32 s38, s38, 8
	v_ashrrev_i32_e32 v140, 4, v0
	v_lshlrev_b32_e32 v0, 4, v0
	s_addk_i32 s38, 0x6000
	v_and_b32_e32 v0, 0xf0, v0
	v_or_b32_e32 v142, s38, v0
	v_mul_f32_e32 v0, 0xba38aa3b, v126
	v_mul_f32_e32 v126, 0xba38aa3b, v127
	v_exp_f32_e32 v126, v126
	v_mul_f32_e32 v127, 0xba38aa3b, v128
	v_exp_f32_e32 v127, v127
	v_exp_f32_e32 v0, v0
	v_mul_f32_e32 v128, 0xba38aa3b, v129
	v_add_f32_e32 v126, 1.0, v126
	v_exp_f32_e32 v128, v128
	v_rcp_f32_e32 v126, v126
	v_add_f32_e32 v127, 1.0, v127
	v_add_f32_e32 v0, 1.0, v0
	v_rcp_f32_e32 v127, v127
	v_rcp_f32_e32 v0, v0
	v_add_f32_e32 v128, 1.0, v128
	v_rcp_f32_e32 v128, v128
	v_fma_f32 v126, v126, s49, 0.5
	v_max_f32_e32 v126, 1.0, v126
	v_cvt_u32_f32_e32 v129, v126
	v_fma_f32 v126, v127, s49, 0.5
	v_fma_f32 v0, v0, s49, 0.5
	v_max_f32_e32 v126, 1.0, v126
	v_max_f32_e32 v0, 1.0, v0
	v_cvt_u32_f32_sdwa v144, v126 dst_sel:WORD_1 dst_unused:UNUSED_PAD src0_sel:DWORD
	v_fma_f32 v126, v128, s49, 0.5
	v_cvt_u32_f32_e32 v0, v0
	v_max_f32_e32 v126, 1.0, v126
	v_mul_f32_e32 v122, 0xba38aa3b, v122
	v_mul_f32_e32 v123, 0xba38aa3b, v123
	v_cvt_u32_f32_sdwa v128, v126 dst_sel:BYTE_3 dst_unused:UNUSED_PAD src0_sel:DWORD
	v_exp_f32_e32 v145, v122
	v_exp_f32_e32 v123, v123
	v_lshl_or_b32 v0, v129, 8, v0
	v_or3_b32 v122, v0, v144, v128
	v_add_f32_e32 v0, 1.0, v145
	v_add_f32_e32 v123, 1.0, v123
	v_mul_f32_e32 v124, 0xba38aa3b, v124
	v_rcp_f32_e32 v0, v0
	v_rcp_f32_e32 v123, v123
	v_mul_f32_e32 v125, 0xba38aa3b, v125
	v_mul_f32_e32 v118, 0xba38aa3b, v118
	v_mul_f32_e32 v119, 0xba38aa3b, v119
	v_exp_f32_e32 v124, v124
	v_exp_f32_e32 v125, v125
	v_exp_f32_e32 v118, v118
	v_exp_f32_e32 v119, v119
	v_mul_f32_e32 v120, 0xba38aa3b, v120
	v_mul_f32_e32 v121, 0xba38aa3b, v121
	v_exp_f32_e32 v120, v120
	v_exp_f32_e32 v121, v121
	v_fma_f32 v0, v0, s49, 0.5
	v_fma_f32 v123, v123, s49, 0.5
; __device__ __forceinline__ unsigned gate_q8(float g) { return (unsigned)fmaxf(g * 255.0f + 0.5f, 1.0f); }
; __device__ __forceinline__ unsigned gate_pk4(const f32x4& g) { return gate_q8(g[0]) | (gate_q8(g[1]) << 8) | (gate_q8(g[2]) << 16) | (gate_q8(g[3]) << 24); }
;     __device__ __forceinline__ void operator()(const f32x4 (&acc)[2][2][4][2], const pg8::GUnit& u, int wr, int wc, int fr, int fq) const {
;     ...
;             for (int m = 0; m < 4; ++m) { u32x4 w; unsigned wq[4];
; #pragma unroll
;                 for (int bj = 0; bj < 2; ++bj)
; #pragma unroll
;                     for (int n = 0; n < 2; ++n) { f32x4 v = acc[ai][bj][m][n];
; #pragma unroll
;                         for (int j = 0; j < 4; ++j) v[j] = __builtin_amdgcn_rcpf(1.0f + __builtin_amdgcn_exp2f(v[j] * (-LOG2E * G8_DESCALE)));
;                         wq[bj * 2 + n] = gate_pk4(v); }
	v_add_f32_e32 v124, 1.0, v124
	v_max_f32_e32 v0, 1.0, v0
	v_max_f32_e32 v123, 1.0, v123
	v_add_f32_e32 v125, 1.0, v125
	v_add_f32_e32 v118, 1.0, v118
	v_add_f32_e32 v119, 1.0, v119
	v_cvt_u32_f32_e32 v0, v0
	v_cvt_u32_f32_e32 v123, v123
	v_rcp_f32_e32 v124, v124
	v_rcp_f32_e32 v125, v125
	v_rcp_f32_e32 v118, v118
	v_rcp_f32_e32 v119, v119
	v_add_f32_e32 v120, 1.0, v120
	v_add_f32_e32 v121, 1.0, v121
	v_rcp_f32_e32 v120, v120
	v_rcp_f32_e32 v121, v121
	v_lshl_or_b32 v0, v123, 8, v0
	v_fma_f32 v123, v124, s49, 0.5
	v_fma_f32 v124, v125, s49, 0.5
	v_fma_f32 v118, v118, s49, 0.5
	v_fma_f32 v119, v119, s49, 0.5
	v_max_f32_e32 v123, 1.0, v123
	v_max_f32_e32 v124, 1.0, v124
	v_max_f32_e32 v118, 1.0, v118
	v_max_f32_e32 v119, 1.0, v119
	v_fma_f32 v120, v120, s49, 0.5
	v_fma_f32 v121, v121, s49, 0.5
	v_cvt_u32_f32_sdwa v123, v123 dst_sel:WORD_1 dst_unused:UNUSED_PAD src0_sel:DWORD
	v_cvt_u32_f32_sdwa v124, v124 dst_sel:BYTE_3 dst_unused:UNUSED_PAD src0_sel:DWORD
	v_cvt_u32_f32_e32 v118, v118
	v_cvt_u32_f32_e32 v119, v119
	v_max_f32_e32 v120, 1.0, v120
	v_max_f32_e32 v121, 1.0, v121
	v_mul_f32_e32 v114, 0xba38aa3b, v114
	v_cvt_u32_f32_sdwa v120, v120 dst_sel:WORD_1 dst_unused:UNUSED_PAD src0_sel:DWORD
	v_cvt_u32_f32_sdwa v121, v121 dst_sel:BYTE_3 dst_unused:UNUSED_PAD src0_sel:DWORD
	v_exp_f32_e32 v114, v114
	v_or3_b32 v123, v0, v123, v124
	v_lshl_or_b32 v0, v119, 8, v118
	v_or3_b32 v124, v0, v120, v121
	v_add_f32_e32 v0, 1.0, v114
	v_mul_f32_e32 v114, 0xba38aa3b, v115
	v_exp_f32_e32 v114, v114
	v_mul_f32_e32 v115, 0xba38aa3b, v116
	v_rcp_f32_e32 v0, v0
	v_mul_f32_e32 v116, 0xba38aa3b, v117
	v_add_f32_e32 v114, 1.0, v114
	v_rcp_f32_e32 v114, v114
	v_exp_f32_e32 v115, v115
	v_exp_f32_e32 v116, v116
	v_fma_f32 v0, v0, s49, 0.5
	v_fma_f32 v114, v114, s49, 0.5
	v_add_f32_e32 v115, 1.0, v115
	v_max_f32_e32 v0, 1.0, v0
	v_max_f32_e32 v114, 1.0, v114
	v_add_f32_e32 v116, 1.0, v116
	v_cvt_u32_f32_e32 v0, v0
	v_cvt_u32_f32_e32 v114, v114
	v_rcp_f32_e32 v115, v115
	v_rcp_f32_e32 v116, v116
	v_mul_f32_e32 v110, 0xba38aa3b, v110
	v_lshl_or_b32 v0, v114, 8, v0
	v_fma_f32 v114, v115, s49, 0.5
	v_fma_f32 v115, v116, s49, 0.5
	v_max_f32_e32 v114, 1.0, v114
	v_max_f32_e32 v115, 1.0, v115
	v_mul_f32_e32 v111, 0xba38aa3b, v111
	v_cvt_u32_f32_sdwa v114, v114 dst_sel:WORD_1 dst_unused:UNUSED_PAD src0_sel:DWORD
	v_cvt_u32_f32_sdwa v115, v115 dst_sel:BYTE_3 dst_unused:UNUSED_PAD src0_sel:DWORD
	v_exp_f32_e32 v110, v110
	v_exp_f32_e32 v111, v111
	v_mul_f32_e32 v106, 0xba38aa3b, v106
	v_or3_b32 v125, v0, v114, v115
	v_add_f32_e32 v0, 1.0, v110
	v_add_f32_e32 v110, 1.0, v111
	v_mul_f32_e32 v111, 0xba38aa3b, v112
	v_mul_f32_e32 v112, 0xba38aa3b, v113
	v_exp_f32_e32 v111, v111
	v_exp_f32_e32 v112, v112
	v_rcp_f32_e32 v0, v0
	v_rcp_f32_e32 v110, v110
	v_add_f32_e32 v111, 1.0, v111
	v_add_f32_e32 v112, 1.0, v112
	v_rcp_f32_e32 v111, v111
	v_rcp_f32_e32 v112, v112
	v_fma_f32 v0, v0, s49, 0.5
	v_fma_f32 v110, v110, s49, 0.5
	v_max_f32_e32 v0, 1.0, v0
	v_max_f32_e32 v110, 1.0, v110
	v_fma_f32 v111, v111, s49, 0.5
	v_fma_f32 v112, v112, s49, 0.5
	v_cvt_u32_f32_e32 v0, v0
	v_cvt_u32_f32_e32 v110, v110
	v_max_f32_e32 v111, 1.0, v111
	v_max_f32_e32 v112, 1.0, v112
	v_mul_f32_e32 v107, 0xba38aa3b, v107
	v_cvt_u32_f32_sdwa v111, v111 dst_sel:WORD_1 dst_unused:UNUSED_PAD src0_sel:DWORD
	v_cvt_u32_f32_sdwa v112, v112 dst_sel:BYTE_3 dst_unused:UNUSED_PAD src0_sel:DWORD
	v_exp_f32_e32 v113, v106
	v_exp_f32_e32 v107, v107
	v_lshl_or_b32 v0, v110, 8, v0
	v_or3_b32 v106, v0, v111, v112
	v_add_f32_e32 v0, 1.0, v113
	v_add_f32_e32 v107, 1.0, v107
	v_mul_f32_e32 v108, 0xba38aa3b, v108
	v_rcp_f32_e32 v0, v0
	v_rcp_f32_e32 v107, v107
	v_mul_f32_e32 v109, 0xba38aa3b, v109
	v_exp_f32_e32 v108, v108
	v_exp_f32_e32 v109, v109
	v_fma_f32 v0, v0, s49, 0.5
	v_fma_f32 v107, v107, s49, 0.5
	v_add_f32_e32 v108, 1.0, v108
	v_max_f32_e32 v0, 1.0, v0
	v_max_f32_e32 v107, 1.0, v107
	v_add_f32_e32 v109, 1.0, v109
	v_cvt_u32_f32_e32 v0, v0
	v_cvt_u32_f32_e32 v107, v107
	v_rcp_f32_e32 v108, v108
	v_rcp_f32_e32 v109, v109
	v_mul_f32_e32 v102, 0xba38aa3b, v102
	v_lshl_or_b32 v0, v107, 8, v0
	v_fma_f32 v107, v108, s49, 0.5
	v_fma_f32 v108, v109, s49, 0.5
	v_max_f32_e32 v107, 1.0, v107
	v_max_f32_e32 v108, 1.0, v108
	v_mul_f32_e32 v103, 0xba38aa3b, v103
	v_cvt_u32_f32_sdwa v107, v107 dst_sel:WORD_1 dst_unused:UNUSED_PAD src0_sel:DWORD
	v_cvt_u32_f32_sdwa v108, v108 dst_sel:BYTE_3 dst_unused:UNUSED_PAD src0_sel:DWORD
	v_exp_f32_e32 v102, v102
	v_exp_f32_e32 v103, v103
	v_mul_f32_e32 v98, 0xba38aa3b, v98
	v_or3_b32 v107, v0, v107, v108
	v_add_f32_e32 v0, 1.0, v102
	v_add_f32_e32 v102, 1.0, v103
	v_mul_f32_e32 v103, 0xba38aa3b, v104
	v_mul_f32_e32 v104, 0xba38aa3b, v105
	v_mul_f32_e32 v99, 0xba38aa3b, v99
	v_exp_f32_e32 v103, v103
	v_exp_f32_e32 v104, v104
	v_exp_f32_e32 v98, v98
	v_exp_f32_e32 v99, v99
	v_mul_f32_e32 v100, 0xba38aa3b, v100
	v_mul_f32_e32 v101, 0xba38aa3b, v101
	v_exp_f32_e32 v100, v100
	v_exp_f32_e32 v101, v101
	v_rcp_f32_e32 v0, v0
	v_rcp_f32_e32 v102, v102
	v_add_f32_e32 v103, 1.0, v103
	v_add_f32_e32 v104, 1.0, v104
	v_add_f32_e32 v98, 1.0, v98
	v_add_f32_e32 v99, 1.0, v99
	v_rcp_f32_e32 v103, v103
	v_rcp_f32_e32 v104, v104
	v_rcp_f32_e32 v98, v98
	v_rcp_f32_e32 v99, v99
	v_add_f32_e32 v100, 1.0, v100
	v_add_f32_e32 v101, 1.0, v101
	v_rcp_f32_e32 v100, v100
	v_rcp_f32_e32 v101, v101
	v_fma_f32 v0, v0, s49, 0.5
	v_fma_f32 v102, v102, s49, 0.5
	v_max_f32_e32 v0, 1.0, v0
	v_max_f32_e32 v102, 1.0, v102
	v_fma_f32 v103, v103, s49, 0.5
	v_fma_f32 v104, v104, s49, 0.5
	v_fma_f32 v98, v98, s49, 0.5
	v_fma_f32 v99, v99, s49, 0.5
	v_cvt_u32_f32_e32 v0, v0
	v_cvt_u32_f32_e32 v102, v102
	v_max_f32_e32 v103, 1.0, v103
; __device__ __forceinline__ unsigned gate_q8(float g) { return (unsigned)fmaxf(g * 255.0f + 0.5f, 1.0f); }
; __device__ __forceinline__ unsigned gate_pk4(const f32x4& g) { return gate_q8(g[0]) | (gate_q8(g[1]) << 8) | (gate_q8(g[2]) << 16) | (gate_q8(g[3]) << 24); }
;     __device__ __forceinline__ void operator()(const f32x4 (&acc)[2][2][4][2], const pg8::GUnit& u, int wr, int wc, int fr, int fq) const {
;     ...
;             for (int m = 0; m < 4; ++m) { u32x4 w; unsigned wq[4];
; #pragma unroll
;                 for (int bj = 0; bj < 2; ++bj)
; #pragma unroll
;                     for (int n = 0; n < 2; ++n) { f32x4 v = acc[ai][bj][m][n];
; #pragma unroll
;                         for (int j = 0; j < 4; ++j) v[j] = __builtin_amdgcn_rcpf(1.0f + __builtin_amdgcn_exp2f(v[j] * (-LOG2E * G8_DESCALE)));
;                         wq[bj * 2 + n] = gate_pk4(v); }
	v_max_f32_e32 v104, 1.0, v104
	v_max_f32_e32 v98, 1.0, v98
	v_max_f32_e32 v99, 1.0, v99
	v_fma_f32 v100, v100, s49, 0.5
	v_fma_f32 v101, v101, s49, 0.5
	v_cvt_u32_f32_sdwa v103, v103 dst_sel:WORD_1 dst_unused:UNUSED_PAD src0_sel:DWORD
	v_cvt_u32_f32_sdwa v104, v104 dst_sel:BYTE_3 dst_unused:UNUSED_PAD src0_sel:DWORD
	v_cvt_u32_f32_e32 v98, v98
	v_cvt_u32_f32_e32 v99, v99
	v_max_f32_e32 v100, 1.0, v100
	v_max_f32_e32 v101, 1.0, v101
	v_cvt_u32_f32_sdwa v100, v100 dst_sel:WORD_1 dst_unused:UNUSED_PAD src0_sel:DWORD
	v_cvt_u32_f32_sdwa v101, v101 dst_sel:BYTE_3 dst_unused:UNUSED_PAD src0_sel:DWORD
	v_lshl_or_b32 v0, v102, 8, v0
	v_or3_b32 v108, v0, v103, v104
	v_lshl_or_b32 v0, v99, 8, v98
	v_or3_b32 v109, v0, v100, v101
	v_mul_f32_e32 v0, 0xba38aa3b, v94
	v_mul_f32_e32 v94, 0xba38aa3b, v95
	v_exp_f32_e32 v0, v0
	v_exp_f32_e32 v98, v94
	v_mul_f32_e32 v96, 0xba38aa3b, v96
	v_mul_f32_e32 v97, 0xba38aa3b, v97
	v_exp_f32_e32 v96, v96
	v_exp_f32_e32 v97, v97
	v_add_f32_e32 v0, 1.0, v0
	v_add_f32_e32 v98, 1.0, v98
	v_rcp_f32_e32 v0, v0
	v_rcp_f32_e32 v98, v98
	v_add_f32_e32 v96, 1.0, v96
	v_add_f32_e32 v97, 1.0, v97
	v_rcp_f32_e32 v96, v96
	v_rcp_f32_e32 v97, v97
	v_fma_f32 v0, v0, s49, 0.5
	v_fma_f32 v98, v98, s49, 0.5
	v_max_f32_e32 v0, 1.0, v0
	v_max_f32_e32 v98, 1.0, v98
	v_fma_f32 v96, v96, s49, 0.5
	v_fma_f32 v97, v97, s49, 0.5
	v_cvt_u32_f32_e32 v0, v0
	v_cvt_u32_f32_e32 v98, v98
	v_max_f32_e32 v96, 1.0, v96
	v_max_f32_e32 v97, 1.0, v97
	v_mul_f32_e32 v90, 0xba38aa3b, v90
	v_mul_f32_e32 v91, 0xba38aa3b, v91
	v_cvt_u32_f32_sdwa v96, v96 dst_sel:WORD_1 dst_unused:UNUSED_PAD src0_sel:DWORD
	v_cvt_u32_f32_sdwa v97, v97 dst_sel:BYTE_3 dst_unused:UNUSED_PAD src0_sel:DWORD
	v_exp_f32_e32 v99, v90
	v_exp_f32_e32 v91, v91
	v_lshl_or_b32 v0, v98, 8, v0
	v_or3_b32 v90, v0, v96, v97
	v_add_f32_e32 v0, 1.0, v99
	v_add_f32_e32 v91, 1.0, v91
	v_mul_f32_e32 v92, 0xba38aa3b, v92
	v_rcp_f32_e32 v0, v0
	v_rcp_f32_e32 v91, v91
	v_mul_f32_e32 v93, 0xba38aa3b, v93
	v_exp_f32_e32 v92, v92
	v_exp_f32_e32 v93, v93
	v_fma_f32 v0, v0, s49, 0.5
	v_fma_f32 v91, v91, s49, 0.5
	v_add_f32_e32 v92, 1.0, v92
	v_max_f32_e32 v0, 1.0, v0
	v_max_f32_e32 v91, 1.0, v91
	v_add_f32_e32 v93, 1.0, v93
	v_cvt_u32_f32_e32 v0, v0
	v_cvt_u32_f32_e32 v91, v91
	v_rcp_f32_e32 v92, v92
	v_rcp_f32_e32 v93, v93
	v_mul_f32_e32 v86, 0xba38aa3b, v86
	v_lshl_or_b32 v0, v91, 8, v0
	v_fma_f32 v91, v92, s49, 0.5
	v_fma_f32 v92, v93, s49, 0.5
	v_max_f32_e32 v91, 1.0, v91
	v_max_f32_e32 v92, 1.0, v92
	v_mul_f32_e32 v87, 0xba38aa3b, v87
	v_cvt_u32_f32_sdwa v91, v91 dst_sel:WORD_1 dst_unused:UNUSED_PAD src0_sel:DWORD
	v_cvt_u32_f32_sdwa v92, v92 dst_sel:BYTE_3 dst_unused:UNUSED_PAD src0_sel:DWORD
	v_exp_f32_e32 v86, v86
	v_exp_f32_e32 v87, v87
	v_mul_f32_e32 v82, 0xba38aa3b, v82
	v_or3_b32 v91, v0, v91, v92
	v_add_f32_e32 v0, 1.0, v86
	v_add_f32_e32 v86, 1.0, v87
	v_mul_f32_e32 v87, 0xba38aa3b, v88
	v_mul_f32_e32 v88, 0xba38aa3b, v89
	v_mul_f32_e32 v83, 0xba38aa3b, v83
	v_exp_f32_e32 v87, v87
	v_exp_f32_e32 v88, v88
	v_exp_f32_e32 v82, v82
	v_exp_f32_e32 v83, v83
	v_mul_f32_e32 v84, 0xba38aa3b, v84
	v_mul_f32_e32 v85, 0xba38aa3b, v85
	v_exp_f32_e32 v84, v84
	v_exp_f32_e32 v85, v85
	v_rcp_f32_e32 v0, v0
	v_rcp_f32_e32 v86, v86
	v_add_f32_e32 v87, 1.0, v87
	v_add_f32_e32 v88, 1.0, v88
	v_add_f32_e32 v82, 1.0, v82
	v_add_f32_e32 v83, 1.0, v83
	v_rcp_f32_e32 v87, v87
	v_rcp_f32_e32 v88, v88
	v_rcp_f32_e32 v82, v82
	v_rcp_f32_e32 v83, v83
	v_add_f32_e32 v84, 1.0, v84
	v_add_f32_e32 v85, 1.0, v85
	v_rcp_f32_e32 v84, v84
	v_rcp_f32_e32 v85, v85
	v_fma_f32 v0, v0, s49, 0.5
	v_fma_f32 v86, v86, s49, 0.5
	v_max_f32_e32 v0, 1.0, v0
	v_max_f32_e32 v86, 1.0, v86
	v_fma_f32 v87, v87, s49, 0.5
	v_fma_f32 v88, v88, s49, 0.5
	v_fma_f32 v82, v82, s49, 0.5
	v_fma_f32 v83, v83, s49, 0.5
	v_cvt_u32_f32_e32 v0, v0
	v_cvt_u32_f32_e32 v86, v86
	v_max_f32_e32 v87, 1.0, v87
	v_max_f32_e32 v88, 1.0, v88
	v_max_f32_e32 v82, 1.0, v82
	v_max_f32_e32 v83, 1.0, v83
	v_fma_f32 v84, v84, s49, 0.5
	v_fma_f32 v85, v85, s49, 0.5
	v_cvt_u32_f32_sdwa v87, v87 dst_sel:WORD_1 dst_unused:UNUSED_PAD src0_sel:DWORD
	v_cvt_u32_f32_sdwa v88, v88 dst_sel:BYTE_3 dst_unused:UNUSED_PAD src0_sel:DWORD
	v_cvt_u32_f32_e32 v82, v82
	v_cvt_u32_f32_e32 v83, v83
	v_max_f32_e32 v84, 1.0, v84
	v_max_f32_e32 v85, 1.0, v85
	v_cvt_u32_f32_sdwa v84, v84 dst_sel:WORD_1 dst_unused:UNUSED_PAD src0_sel:DWORD
	v_cvt_u32_f32_sdwa v85, v85 dst_sel:BYTE_3 dst_unused:UNUSED_PAD src0_sel:DWORD
	v_lshl_or_b32 v0, v86, 8, v0
	v_or3_b32 v92, v0, v87, v88
	v_lshl_or_b32 v0, v83, 8, v82
	v_or3_b32 v93, v0, v84, v85
	v_mul_f32_e32 v0, 0xba38aa3b, v78
	v_mul_f32_e32 v78, 0xba38aa3b, v79
	v_exp_f32_e32 v0, v0
	v_exp_f32_e32 v82, v78
	v_mul_f32_e32 v80, 0xba38aa3b, v80
	v_mul_f32_e32 v81, 0xba38aa3b, v81
	v_exp_f32_e32 v80, v80
	v_exp_f32_e32 v81, v81
	v_add_f32_e32 v0, 1.0, v0
	v_add_f32_e32 v82, 1.0, v82
	v_rcp_f32_e32 v0, v0
	v_rcp_f32_e32 v82, v82
	v_add_f32_e32 v80, 1.0, v80
	v_add_f32_e32 v81, 1.0, v81
	v_rcp_f32_e32 v80, v80
	v_rcp_f32_e32 v81, v81
	v_fma_f32 v0, v0, s49, 0.5
	v_fma_f32 v82, v82, s49, 0.5
	v_max_f32_e32 v0, 1.0, v0
	v_max_f32_e32 v82, 1.0, v82
	v_fma_f32 v80, v80, s49, 0.5
	v_fma_f32 v81, v81, s49, 0.5
	v_cvt_u32_f32_e32 v0, v0
	v_cvt_u32_f32_e32 v82, v82
	v_max_f32_e32 v80, 1.0, v80
	v_max_f32_e32 v81, 1.0, v81
	v_mul_f32_e32 v74, 0xba38aa3b, v74
	v_mul_f32_e32 v75, 0xba38aa3b, v75
	v_cvt_u32_f32_sdwa v80, v80 dst_sel:WORD_1 dst_unused:UNUSED_PAD src0_sel:DWORD
	v_cvt_u32_f32_sdwa v81, v81 dst_sel:BYTE_3 dst_unused:UNUSED_PAD src0_sel:DWORD
	v_exp_f32_e32 v83, v74
	v_exp_f32_e32 v75, v75
	v_lshl_or_b32 v0, v82, 8, v0
	v_or3_b32 v74, v0, v80, v81
; __device__ __forceinline__ unsigned gate_q8(float g) { return (unsigned)fmaxf(g * 255.0f + 0.5f, 1.0f); }
; __device__ __forceinline__ unsigned gate_pk4(const f32x4& g) { return gate_q8(g[0]) | (gate_q8(g[1]) << 8) | (gate_q8(g[2]) << 16) | (gate_q8(g[3]) << 24); }
;     __device__ __forceinline__ void operator()(const f32x4 (&acc)[2][2][4][2], const pg8::GUnit& u, int wr, int wc, int fr, int fq) const {
;     ...
;             for (int m = 0; m < 4; ++m) { u32x4 w; unsigned wq[4];
; #pragma unroll
;                 for (int bj = 0; bj < 2; ++bj)
; #pragma unroll
;                     for (int n = 0; n < 2; ++n) { f32x4 v = acc[ai][bj][m][n];
; #pragma unroll
;                         for (int j = 0; j < 4; ++j) v[j] = __builtin_amdgcn_rcpf(1.0f + __builtin_amdgcn_exp2f(v[j] * (-LOG2E * G8_DESCALE)));
;                         wq[bj * 2 + n] = gate_pk4(v); }
	v_add_f32_e32 v0, 1.0, v83
	v_add_f32_e32 v75, 1.0, v75
	v_mul_f32_e32 v76, 0xba38aa3b, v76
	v_rcp_f32_e32 v0, v0
	v_rcp_f32_e32 v75, v75
	v_mul_f32_e32 v77, 0xba38aa3b, v77
	v_exp_f32_e32 v76, v76
	v_exp_f32_e32 v77, v77
	v_fma_f32 v0, v0, s49, 0.5
	v_fma_f32 v75, v75, s49, 0.5
	v_add_f32_e32 v76, 1.0, v76
	v_max_f32_e32 v0, 1.0, v0
	v_max_f32_e32 v75, 1.0, v75
	v_add_f32_e32 v77, 1.0, v77
	v_cvt_u32_f32_e32 v0, v0
	v_cvt_u32_f32_e32 v75, v75
	v_rcp_f32_e32 v76, v76
	v_rcp_f32_e32 v77, v77
	v_mul_f32_e32 v70, 0xba38aa3b, v70
	v_lshl_or_b32 v0, v75, 8, v0
	v_fma_f32 v75, v76, s49, 0.5
	v_fma_f32 v76, v77, s49, 0.5
	v_max_f32_e32 v75, 1.0, v75
	v_max_f32_e32 v76, 1.0, v76
	v_mul_f32_e32 v71, 0xba38aa3b, v71
	v_cvt_u32_f32_sdwa v75, v75 dst_sel:WORD_1 dst_unused:UNUSED_PAD src0_sel:DWORD
	v_cvt_u32_f32_sdwa v76, v76 dst_sel:BYTE_3 dst_unused:UNUSED_PAD src0_sel:DWORD
	v_exp_f32_e32 v70, v70
	v_exp_f32_e32 v71, v71
	v_mul_f32_e32 v66, 0xba38aa3b, v66
	v_or3_b32 v75, v0, v75, v76
	v_add_f32_e32 v0, 1.0, v70
	v_add_f32_e32 v70, 1.0, v71
	v_mul_f32_e32 v71, 0xba38aa3b, v72
	v_mul_f32_e32 v72, 0xba38aa3b, v73
	v_mul_f32_e32 v67, 0xba38aa3b, v67
	v_exp_f32_e32 v71, v71
	v_exp_f32_e32 v72, v72
	v_exp_f32_e32 v66, v66
	v_exp_f32_e32 v67, v67
	v_mul_f32_e32 v68, 0xba38aa3b, v68
	v_mul_f32_e32 v69, 0xba38aa3b, v69
	v_exp_f32_e32 v68, v68
	v_exp_f32_e32 v69, v69
	v_rcp_f32_e32 v0, v0
	v_rcp_f32_e32 v70, v70
	v_add_f32_e32 v71, 1.0, v71
	v_add_f32_e32 v72, 1.0, v72
	v_add_f32_e32 v66, 1.0, v66
	v_add_f32_e32 v67, 1.0, v67
	v_rcp_f32_e32 v71, v71
	v_rcp_f32_e32 v72, v72
	v_rcp_f32_e32 v66, v66
	v_rcp_f32_e32 v67, v67
	v_add_f32_e32 v68, 1.0, v68
	v_add_f32_e32 v69, 1.0, v69
	v_rcp_f32_e32 v68, v68
	v_rcp_f32_e32 v69, v69
	v_fma_f32 v0, v0, s49, 0.5
	v_fma_f32 v70, v70, s49, 0.5
	v_max_f32_e32 v0, 1.0, v0
	v_max_f32_e32 v70, 1.0, v70
	v_fma_f32 v71, v71, s49, 0.5
	v_fma_f32 v72, v72, s49, 0.5
	v_fma_f32 v66, v66, s49, 0.5
	v_fma_f32 v67, v67, s49, 0.5
	v_cvt_u32_f32_e32 v0, v0
	v_cvt_u32_f32_e32 v70, v70
	v_max_f32_e32 v71, 1.0, v71
	v_max_f32_e32 v72, 1.0, v72
	v_max_f32_e32 v66, 1.0, v66
	v_max_f32_e32 v67, 1.0, v67
	v_fma_f32 v68, v68, s49, 0.5
	v_fma_f32 v69, v69, s49, 0.5
	v_cvt_u32_f32_sdwa v71, v71 dst_sel:WORD_1 dst_unused:UNUSED_PAD src0_sel:DWORD
	v_cvt_u32_f32_sdwa v72, v72 dst_sel:BYTE_3 dst_unused:UNUSED_PAD src0_sel:DWORD
	v_cvt_u32_f32_e32 v66, v66
	v_cvt_u32_f32_e32 v67, v67
	v_max_f32_e32 v68, 1.0, v68
	v_max_f32_e32 v69, 1.0, v69
	v_cvt_u32_f32_sdwa v68, v68 dst_sel:WORD_1 dst_unused:UNUSED_PAD src0_sel:DWORD
	v_cvt_u32_f32_sdwa v69, v69 dst_sel:BYTE_3 dst_unused:UNUSED_PAD src0_sel:DWORD
	v_lshl_or_b32 v0, v70, 8, v0
	v_or3_b32 v76, v0, v71, v72
	v_lshl_or_b32 v0, v67, 8, v66
	v_or3_b32 v77, v0, v68, v69
	v_mul_f32_e32 v0, 0xba38aa3b, v62
	v_mul_f32_e32 v62, 0xba38aa3b, v63
	v_exp_f32_e32 v0, v0
	v_exp_f32_e32 v66, v62
	v_mul_f32_e32 v64, 0xba38aa3b, v64
	v_mul_f32_e32 v65, 0xba38aa3b, v65
	v_exp_f32_e32 v64, v64
	v_exp_f32_e32 v65, v65
	v_add_f32_e32 v0, 1.0, v0
	v_add_f32_e32 v66, 1.0, v66
	v_rcp_f32_e32 v0, v0
	v_rcp_f32_e32 v66, v66
	v_add_f32_e32 v64, 1.0, v64
	v_add_f32_e32 v65, 1.0, v65
	v_rcp_f32_e32 v64, v64
	v_rcp_f32_e32 v65, v65
	v_fma_f32 v0, v0, s49, 0.5
	v_fma_f32 v66, v66, s49, 0.5
	v_max_f32_e32 v0, 1.0, v0
	v_max_f32_e32 v66, 1.0, v66
	v_fma_f32 v64, v64, s49, 0.5
	v_fma_f32 v65, v65, s49, 0.5
	v_cvt_u32_f32_e32 v0, v0
	v_cvt_u32_f32_e32 v66, v66
	v_max_f32_e32 v64, 1.0, v64
	v_max_f32_e32 v65, 1.0, v65
	v_mul_f32_e32 v58, 0xba38aa3b, v58
	v_mul_f32_e32 v59, 0xba38aa3b, v59
	v_cvt_u32_f32_sdwa v64, v64 dst_sel:WORD_1 dst_unused:UNUSED_PAD src0_sel:DWORD
	v_cvt_u32_f32_sdwa v65, v65 dst_sel:BYTE_3 dst_unused:UNUSED_PAD src0_sel:DWORD
	v_exp_f32_e32 v67, v58
	v_exp_f32_e32 v59, v59
	v_lshl_or_b32 v0, v66, 8, v0
	v_or3_b32 v58, v0, v64, v65
	v_add_f32_e32 v0, 1.0, v67
	v_add_f32_e32 v59, 1.0, v59
	v_mul_f32_e32 v60, 0xba38aa3b, v60
	v_rcp_f32_e32 v0, v0
	v_rcp_f32_e32 v59, v59
	v_mul_f32_e32 v61, 0xba38aa3b, v61
	v_exp_f32_e32 v60, v60
	v_exp_f32_e32 v61, v61
	v_fma_f32 v0, v0, s49, 0.5
	v_fma_f32 v59, v59, s49, 0.5
	v_add_f32_e32 v60, 1.0, v60
	v_max_f32_e32 v0, 1.0, v0
	v_max_f32_e32 v59, 1.0, v59
	v_add_f32_e32 v61, 1.0, v61
	v_cvt_u32_f32_e32 v0, v0
	v_cvt_u32_f32_e32 v59, v59
	v_rcp_f32_e32 v60, v60
	v_rcp_f32_e32 v61, v61
	v_mul_f32_e32 v54, 0xba38aa3b, v54
	v_lshl_or_b32 v0, v59, 8, v0
	v_fma_f32 v59, v60, s49, 0.5
	v_fma_f32 v60, v61, s49, 0.5
	v_max_f32_e32 v59, 1.0, v59
	v_max_f32_e32 v60, 1.0, v60
	v_mul_f32_e32 v55, 0xba38aa3b, v55
	v_cvt_u32_f32_sdwa v59, v59 dst_sel:WORD_1 dst_unused:UNUSED_PAD src0_sel:DWORD
	v_cvt_u32_f32_sdwa v60, v60 dst_sel:BYTE_3 dst_unused:UNUSED_PAD src0_sel:DWORD
	v_exp_f32_e32 v54, v54
	v_exp_f32_e32 v55, v55
	v_mul_f32_e32 v50, 0xba38aa3b, v50
	v_or3_b32 v59, v0, v59, v60
	v_add_f32_e32 v0, 1.0, v54
	v_add_f32_e32 v54, 1.0, v55
	v_mul_f32_e32 v55, 0xba38aa3b, v56
	v_mul_f32_e32 v56, 0xba38aa3b, v57
	v_mul_f32_e32 v51, 0xba38aa3b, v51
	v_exp_f32_e32 v55, v55
	v_exp_f32_e32 v56, v56
	v_exp_f32_e32 v50, v50
	v_exp_f32_e32 v51, v51
	v_mul_f32_e32 v52, 0xba38aa3b, v52
	v_mul_f32_e32 v53, 0xba38aa3b, v53
	v_exp_f32_e32 v52, v52
	v_exp_f32_e32 v53, v53
	v_rcp_f32_e32 v0, v0
	v_rcp_f32_e32 v54, v54
	v_add_f32_e32 v55, 1.0, v55
	v_add_f32_e32 v56, 1.0, v56
	v_add_f32_e32 v50, 1.0, v50
	v_add_f32_e32 v51, 1.0, v51
	v_rcp_f32_e32 v55, v55
	v_rcp_f32_e32 v56, v56
	v_rcp_f32_e32 v50, v50
	v_rcp_f32_e32 v51, v51
	v_add_f32_e32 v52, 1.0, v52
	v_add_f32_e32 v53, 1.0, v53
	v_rcp_f32_e32 v52, v52
	v_rcp_f32_e32 v53, v53
	v_fma_f32 v0, v0, s49, 0.5
	v_fma_f32 v54, v54, s49, 0.5
	v_max_f32_e32 v0, 1.0, v0
; __device__ __forceinline__ unsigned gate_q8(float g) { return (unsigned)fmaxf(g * 255.0f + 0.5f, 1.0f); }
; __device__ __forceinline__ unsigned gate_pk4(const f32x4& g) { return gate_q8(g[0]) | (gate_q8(g[1]) << 8) | (gate_q8(g[2]) << 16) | (gate_q8(g[3]) << 24); }
;     __device__ __forceinline__ void operator()(const f32x4 (&acc)[2][2][4][2], const pg8::GUnit& u, int wr, int wc, int fr, int fq) const {
;     ...
;                     for (int n = 0; n < 2; ++n) { f32x4 v = acc[ai][bj][m][n];
; #pragma unroll
;                         for (int j = 0; j < 4; ++j) v[j] = __builtin_amdgcn_rcpf(1.0f + __builtin_amdgcn_exp2f(v[j] * (-LOG2E * G8_DESCALE)));
;                         wq[bj * 2 + n] = gate_pk4(v); }
	v_max_f32_e32 v54, 1.0, v54
	v_fma_f32 v55, v55, s49, 0.5
	v_fma_f32 v56, v56, s49, 0.5
	v_fma_f32 v50, v50, s49, 0.5
	v_fma_f32 v51, v51, s49, 0.5
	v_cvt_u32_f32_e32 v0, v0
	v_cvt_u32_f32_e32 v54, v54
	v_max_f32_e32 v55, 1.0, v55
	v_max_f32_e32 v56, 1.0, v56
	v_max_f32_e32 v50, 1.0, v50
	v_max_f32_e32 v51, 1.0, v51
	v_fma_f32 v52, v52, s49, 0.5
	v_fma_f32 v53, v53, s49, 0.5
	v_cvt_u32_f32_sdwa v55, v55 dst_sel:WORD_1 dst_unused:UNUSED_PAD src0_sel:DWORD
	v_cvt_u32_f32_sdwa v56, v56 dst_sel:BYTE_3 dst_unused:UNUSED_PAD src0_sel:DWORD
	v_cvt_u32_f32_e32 v50, v50
	v_cvt_u32_f32_e32 v51, v51
	v_max_f32_e32 v52, 1.0, v52
	v_max_f32_e32 v53, 1.0, v53
	v_cvt_u32_f32_sdwa v52, v52 dst_sel:WORD_1 dst_unused:UNUSED_PAD src0_sel:DWORD
	v_cvt_u32_f32_sdwa v53, v53 dst_sel:BYTE_3 dst_unused:UNUSED_PAD src0_sel:DWORD
	v_lshl_or_b32 v0, v54, 8, v0
	v_or3_b32 v60, v0, v55, v56
	v_lshl_or_b32 v0, v51, 8, v50
	v_or3_b32 v61, v0, v52, v53
	v_mul_f32_e32 v0, 0xba38aa3b, v46
	v_mul_f32_e32 v46, 0xba38aa3b, v47
	v_exp_f32_e32 v0, v0
	v_exp_f32_e32 v50, v46
	v_mul_f32_e32 v48, 0xba38aa3b, v48
	v_mul_f32_e32 v49, 0xba38aa3b, v49
	v_exp_f32_e32 v48, v48
	v_exp_f32_e32 v49, v49
	v_add_f32_e32 v0, 1.0, v0
	v_add_f32_e32 v50, 1.0, v50
	v_rcp_f32_e32 v0, v0
	v_rcp_f32_e32 v50, v50
	v_add_f32_e32 v48, 1.0, v48
	v_add_f32_e32 v49, 1.0, v49
	v_rcp_f32_e32 v48, v48
	v_rcp_f32_e32 v49, v49
	v_fma_f32 v0, v0, s49, 0.5
	v_fma_f32 v50, v50, s49, 0.5
	v_max_f32_e32 v0, 1.0, v0
	v_max_f32_e32 v50, 1.0, v50
	v_fma_f32 v48, v48, s49, 0.5
	v_fma_f32 v49, v49, s49, 0.5
	v_cvt_u32_f32_e32 v0, v0
	v_cvt_u32_f32_e32 v50, v50
	v_max_f32_e32 v48, 1.0, v48
	v_max_f32_e32 v49, 1.0, v49
	v_mul_f32_e32 v42, 0xba38aa3b, v42
	v_mul_f32_e32 v43, 0xba38aa3b, v43
	v_cvt_u32_f32_sdwa v48, v48 dst_sel:WORD_1 dst_unused:UNUSED_PAD src0_sel:DWORD
	v_cvt_u32_f32_sdwa v49, v49 dst_sel:BYTE_3 dst_unused:UNUSED_PAD src0_sel:DWORD
	v_exp_f32_e32 v51, v42
	v_exp_f32_e32 v43, v43
	v_lshl_or_b32 v0, v50, 8, v0
	v_or3_b32 v42, v0, v48, v49
	v_add_f32_e32 v0, 1.0, v51
	v_add_f32_e32 v43, 1.0, v43
	v_mul_f32_e32 v44, 0xba38aa3b, v44
	v_rcp_f32_e32 v0, v0
	v_rcp_f32_e32 v43, v43
	v_mul_f32_e32 v45, 0xba38aa3b, v45
	v_exp_f32_e32 v44, v44
	v_exp_f32_e32 v45, v45
	v_fma_f32 v0, v0, s49, 0.5
	v_fma_f32 v43, v43, s49, 0.5
	v_add_f32_e32 v44, 1.0, v44
	v_max_f32_e32 v0, 1.0, v0
	v_max_f32_e32 v43, 1.0, v43
	v_add_f32_e32 v45, 1.0, v45
	v_cvt_u32_f32_e32 v0, v0
	v_cvt_u32_f32_e32 v43, v43
	v_rcp_f32_e32 v44, v44
	v_rcp_f32_e32 v45, v45
	v_mul_f32_e32 v38, 0xba38aa3b, v38
	v_lshl_or_b32 v0, v43, 8, v0
	v_fma_f32 v43, v44, s49, 0.5
	v_fma_f32 v44, v45, s49, 0.5
	v_max_f32_e32 v43, 1.0, v43
	v_max_f32_e32 v44, 1.0, v44
	v_mul_f32_e32 v39, 0xba38aa3b, v39
	v_cvt_u32_f32_sdwa v43, v43 dst_sel:WORD_1 dst_unused:UNUSED_PAD src0_sel:DWORD
	v_cvt_u32_f32_sdwa v44, v44 dst_sel:BYTE_3 dst_unused:UNUSED_PAD src0_sel:DWORD
	v_exp_f32_e32 v38, v38
	v_exp_f32_e32 v39, v39
	v_mul_f32_e32 v34, 0xba38aa3b, v34
	v_or3_b32 v43, v0, v43, v44
	v_add_f32_e32 v0, 1.0, v38
	v_add_f32_e32 v38, 1.0, v39
	v_mul_f32_e32 v39, 0xba38aa3b, v40
	v_mul_f32_e32 v40, 0xba38aa3b, v41
	v_mul_f32_e32 v35, 0xba38aa3b, v35
	v_exp_f32_e32 v39, v39
	v_exp_f32_e32 v40, v40
	v_exp_f32_e32 v34, v34
	v_exp_f32_e32 v35, v35
	v_mul_f32_e32 v36, 0xba38aa3b, v36
	v_mul_f32_e32 v37, 0xba38aa3b, v37
	v_exp_f32_e32 v36, v36
	v_exp_f32_e32 v37, v37
	v_rcp_f32_e32 v0, v0
	v_rcp_f32_e32 v38, v38
	v_add_f32_e32 v39, 1.0, v39
	v_add_f32_e32 v40, 1.0, v40
	v_add_f32_e32 v34, 1.0, v34
	v_add_f32_e32 v35, 1.0, v35
	v_rcp_f32_e32 v39, v39
	v_rcp_f32_e32 v40, v40
	v_rcp_f32_e32 v34, v34
	v_rcp_f32_e32 v35, v35
	v_add_f32_e32 v36, 1.0, v36
	v_add_f32_e32 v37, 1.0, v37
	v_rcp_f32_e32 v36, v36
	v_rcp_f32_e32 v37, v37
	v_fma_f32 v0, v0, s49, 0.5
	v_fma_f32 v38, v38, s49, 0.5
	v_max_f32_e32 v0, 1.0, v0
	v_max_f32_e32 v38, 1.0, v38
	v_fma_f32 v39, v39, s49, 0.5
	v_fma_f32 v40, v40, s49, 0.5
	v_fma_f32 v34, v34, s49, 0.5
	v_fma_f32 v35, v35, s49, 0.5
	v_cvt_u32_f32_e32 v0, v0
	v_cvt_u32_f32_e32 v38, v38
	v_max_f32_e32 v39, 1.0, v39
	v_max_f32_e32 v40, 1.0, v40
	v_max_f32_e32 v34, 1.0, v34
	v_max_f32_e32 v35, 1.0, v35
	v_fma_f32 v36, v36, s49, 0.5
	v_fma_f32 v37, v37, s49, 0.5
	v_cvt_u32_f32_sdwa v39, v39 dst_sel:WORD_1 dst_unused:UNUSED_PAD src0_sel:DWORD
	v_cvt_u32_f32_sdwa v40, v40 dst_sel:BYTE_3 dst_unused:UNUSED_PAD src0_sel:DWORD
	v_cvt_u32_f32_e32 v34, v34
	v_cvt_u32_f32_e32 v35, v35
	v_max_f32_e32 v36, 1.0, v36
	v_max_f32_e32 v37, 1.0, v37
	v_cvt_u32_f32_sdwa v36, v36 dst_sel:WORD_1 dst_unused:UNUSED_PAD src0_sel:DWORD
	v_cvt_u32_f32_sdwa v37, v37 dst_sel:BYTE_3 dst_unused:UNUSED_PAD src0_sel:DWORD
	v_lshl_or_b32 v0, v38, 8, v0
	v_or3_b32 v44, v0, v39, v40
	v_lshl_or_b32 v0, v35, 8, v34
	v_or3_b32 v45, v0, v36, v37
	v_mul_f32_e32 v0, 0xba38aa3b, v30
	v_mul_f32_e32 v30, 0xba38aa3b, v31
	v_exp_f32_e32 v0, v0
	v_exp_f32_e32 v34, v30
	v_mul_f32_e32 v32, 0xba38aa3b, v32
	v_mul_f32_e32 v33, 0xba38aa3b, v33
	v_exp_f32_e32 v32, v32
	v_exp_f32_e32 v33, v33
	v_add_f32_e32 v0, 1.0, v0
	v_add_f32_e32 v34, 1.0, v34
	v_rcp_f32_e32 v0, v0
	v_rcp_f32_e32 v34, v34
	v_add_f32_e32 v32, 1.0, v32
	v_add_f32_e32 v33, 1.0, v33
	v_rcp_f32_e32 v32, v32
	v_rcp_f32_e32 v33, v33
	v_fma_f32 v0, v0, s49, 0.5
	v_fma_f32 v34, v34, s49, 0.5
	v_max_f32_e32 v0, 1.0, v0
	v_max_f32_e32 v34, 1.0, v34
	v_fma_f32 v32, v32, s49, 0.5
	v_fma_f32 v33, v33, s49, 0.5
	v_cvt_u32_f32_e32 v0, v0
	v_cvt_u32_f32_e32 v34, v34
	v_max_f32_e32 v32, 1.0, v32
	v_max_f32_e32 v33, 1.0, v33
	v_mul_f32_e32 v26, 0xba38aa3b, v26
	v_mul_f32_e32 v27, 0xba38aa3b, v27
	v_cvt_u32_f32_sdwa v32, v32 dst_sel:WORD_1 dst_unused:UNUSED_PAD src0_sel:DWORD
; __device__ __forceinline__ unsigned gate_q8(float g) { return (unsigned)fmaxf(g * 255.0f + 0.5f, 1.0f); }
; __device__ __forceinline__ unsigned gate_pk4(const f32x4& g) { return gate_q8(g[0]) | (gate_q8(g[1]) << 8) | (gate_q8(g[2]) << 16) | (gate_q8(g[3]) << 24); }
;     __device__ __forceinline__ void operator()(const f32x4 (&acc)[2][2][4][2], const pg8::GUnit& u, int wr, int wc, int fr, int fq) const {
;     ...
;                     for (int n = 0; n < 2; ++n) { f32x4 v = acc[ai][bj][m][n];
; #pragma unroll
;                         for (int j = 0; j < 4; ++j) v[j] = __builtin_amdgcn_rcpf(1.0f + __builtin_amdgcn_exp2f(v[j] * (-LOG2E * G8_DESCALE)));
;                         wq[bj * 2 + n] = gate_pk4(v); }
	v_cvt_u32_f32_sdwa v33, v33 dst_sel:BYTE_3 dst_unused:UNUSED_PAD src0_sel:DWORD
	v_exp_f32_e32 v35, v26
	v_exp_f32_e32 v27, v27
	v_lshl_or_b32 v0, v34, 8, v0
	v_or3_b32 v26, v0, v32, v33
	v_add_f32_e32 v0, 1.0, v35
	v_add_f32_e32 v27, 1.0, v27
	v_mul_f32_e32 v28, 0xba38aa3b, v28
	v_rcp_f32_e32 v0, v0
	v_rcp_f32_e32 v27, v27
	v_mul_f32_e32 v29, 0xba38aa3b, v29
	v_exp_f32_e32 v28, v28
	v_exp_f32_e32 v29, v29
	v_fma_f32 v0, v0, s49, 0.5
	v_fma_f32 v27, v27, s49, 0.5
	v_add_f32_e32 v28, 1.0, v28
	v_max_f32_e32 v0, 1.0, v0
	v_max_f32_e32 v27, 1.0, v27
	v_add_f32_e32 v29, 1.0, v29
	v_cvt_u32_f32_e32 v0, v0
	v_cvt_u32_f32_e32 v27, v27
	v_rcp_f32_e32 v28, v28
	v_rcp_f32_e32 v29, v29
	v_mul_f32_e32 v22, 0xba38aa3b, v22
	v_lshl_or_b32 v0, v27, 8, v0
	v_fma_f32 v27, v28, s49, 0.5
	v_fma_f32 v28, v29, s49, 0.5
	v_max_f32_e32 v27, 1.0, v27
	v_max_f32_e32 v28, 1.0, v28
	v_mul_f32_e32 v23, 0xba38aa3b, v23
	v_cvt_u32_f32_sdwa v27, v27 dst_sel:WORD_1 dst_unused:UNUSED_PAD src0_sel:DWORD
	v_cvt_u32_f32_sdwa v28, v28 dst_sel:BYTE_3 dst_unused:UNUSED_PAD src0_sel:DWORD
	v_exp_f32_e32 v22, v22
	v_exp_f32_e32 v23, v23
	v_mul_f32_e32 v18, 0xba38aa3b, v18
	v_or3_b32 v27, v0, v27, v28
	v_add_f32_e32 v0, 1.0, v22
	v_add_f32_e32 v22, 1.0, v23
	v_mul_f32_e32 v23, 0xba38aa3b, v24
	v_mul_f32_e32 v24, 0xba38aa3b, v25
	v_mul_f32_e32 v19, 0xba38aa3b, v19
	v_exp_f32_e32 v23, v23
	v_exp_f32_e32 v24, v24
	v_exp_f32_e32 v18, v18
	v_exp_f32_e32 v19, v19
	v_mul_f32_e32 v20, 0xba38aa3b, v20
	v_mul_f32_e32 v21, 0xba38aa3b, v21
	v_exp_f32_e32 v20, v20
	v_exp_f32_e32 v21, v21
	v_rcp_f32_e32 v0, v0
	v_rcp_f32_e32 v22, v22
	v_add_f32_e32 v23, 1.0, v23
	v_add_f32_e32 v24, 1.0, v24
	v_add_f32_e32 v18, 1.0, v18
	v_add_f32_e32 v19, 1.0, v19
	v_rcp_f32_e32 v23, v23
	v_rcp_f32_e32 v24, v24
	v_rcp_f32_e32 v18, v18
	v_rcp_f32_e32 v19, v19
	v_add_f32_e32 v20, 1.0, v20
	v_add_f32_e32 v21, 1.0, v21
	v_rcp_f32_e32 v20, v20
	v_rcp_f32_e32 v21, v21
	v_fma_f32 v0, v0, s49, 0.5
	v_fma_f32 v22, v22, s49, 0.5
	v_max_f32_e32 v0, 1.0, v0
	v_max_f32_e32 v22, 1.0, v22
	v_fma_f32 v23, v23, s49, 0.5
	v_fma_f32 v24, v24, s49, 0.5
	v_fma_f32 v18, v18, s49, 0.5
	v_fma_f32 v19, v19, s49, 0.5
	v_cvt_u32_f32_e32 v0, v0
	v_cvt_u32_f32_e32 v22, v22
	v_max_f32_e32 v23, 1.0, v23
	v_max_f32_e32 v24, 1.0, v24
	v_max_f32_e32 v18, 1.0, v18
	v_max_f32_e32 v19, 1.0, v19
	v_fma_f32 v20, v20, s49, 0.5
	v_fma_f32 v21, v21, s49, 0.5
	v_cvt_u32_f32_sdwa v23, v23 dst_sel:WORD_1 dst_unused:UNUSED_PAD src0_sel:DWORD
	v_cvt_u32_f32_sdwa v24, v24 dst_sel:BYTE_3 dst_unused:UNUSED_PAD src0_sel:DWORD
	v_cvt_u32_f32_e32 v18, v18
	v_cvt_u32_f32_e32 v19, v19
	v_max_f32_e32 v20, 1.0, v20
	v_max_f32_e32 v21, 1.0, v21
	v_cvt_u32_f32_sdwa v20, v20 dst_sel:WORD_1 dst_unused:UNUSED_PAD src0_sel:DWORD
	v_cvt_u32_f32_sdwa v21, v21 dst_sel:BYTE_3 dst_unused:UNUSED_PAD src0_sel:DWORD
	v_lshl_or_b32 v0, v22, 8, v0
	v_or3_b32 v28, v0, v23, v24
	v_lshl_or_b32 v0, v19, 8, v18
	v_or3_b32 v29, v0, v20, v21
	v_mul_f32_e32 v0, 0xba38aa3b, v14
	v_mul_f32_e32 v14, 0xba38aa3b, v15
	v_exp_f32_e32 v0, v0
	v_exp_f32_e32 v18, v14
	v_mul_f32_e32 v16, 0xba38aa3b, v16
	v_mul_f32_e32 v17, 0xba38aa3b, v17
	v_exp_f32_e32 v16, v16
	v_exp_f32_e32 v17, v17
	v_add_f32_e32 v0, 1.0, v0
	v_add_f32_e32 v18, 1.0, v18
	v_rcp_f32_e32 v0, v0
	v_rcp_f32_e32 v18, v18
	v_add_f32_e32 v16, 1.0, v16
	v_add_f32_e32 v17, 1.0, v17
	v_rcp_f32_e32 v16, v16
	v_rcp_f32_e32 v17, v17
	v_fma_f32 v0, v0, s49, 0.5
	v_fma_f32 v18, v18, s49, 0.5
	v_max_f32_e32 v0, 1.0, v0
	v_max_f32_e32 v18, 1.0, v18
	v_fma_f32 v16, v16, s49, 0.5
	v_fma_f32 v17, v17, s49, 0.5
	v_cvt_u32_f32_e32 v0, v0
	v_cvt_u32_f32_e32 v18, v18
	v_max_f32_e32 v16, 1.0, v16
	v_max_f32_e32 v17, 1.0, v17
	v_mul_f32_e32 v10, 0xba38aa3b, v10
	v_mul_f32_e32 v11, 0xba38aa3b, v11
	v_cvt_u32_f32_sdwa v16, v16 dst_sel:WORD_1 dst_unused:UNUSED_PAD src0_sel:DWORD
	v_cvt_u32_f32_sdwa v17, v17 dst_sel:BYTE_3 dst_unused:UNUSED_PAD src0_sel:DWORD
	v_exp_f32_e32 v19, v10
	v_exp_f32_e32 v11, v11
	v_lshl_or_b32 v0, v18, 8, v0
	v_or3_b32 v10, v0, v16, v17
	v_add_f32_e32 v0, 1.0, v19
	v_add_f32_e32 v11, 1.0, v11
	v_mul_f32_e32 v12, 0xba38aa3b, v12
; #define GAS __attribute__((address_space(1)))
; __device__ __forceinline__ unsigned gate_pk4(const f32x4& g) { return gate_q8(g[0]) | (gate_q8(g[1]) << 8) | (gate_q8(g[2]) << 16) | (gate_q8(g[3]) << 24); }
; #define PG8_WAIT_V(n) asm volatile("s_waitcnt vmcnt(" #n ")" ::: "memory")
; #define PG8_BAR __builtin_amdgcn_s_barrier()
;     ...
;     PG8_WAIT_V(0);
;     if (wr == 0) PG8_BAR;
;     PG8_BAR;
;     __device__ __forceinline__ void operator()(const f32x4 (&acc)[2][2][4][2], const pg8::GUnit& u, int wr, int wc, int fr, int fq) const {
;     ...
;                     for (int n = 0; n < 2; ++n) { f32x4 v = acc[ai][bj][m][n];
; #pragma unroll
;                         for (int j = 0; j < 4; ++j) v[j] = __builtin_amdgcn_rcpf(1.0f + __builtin_amdgcn_exp2f(v[j] * (-LOG2E * G8_DESCALE)));
;                         wq[bj * 2 + n] = gate_pk4(v); }
;                 w.x = wq[0]; w.y = wq[1]; w.z = wq[2]; w.w = wq[3];
;                 *(GAS u32x4*)(gb + (size_t)((ai * 4 + m) * 4) * (INW * 2)) = w; }
	v_rcp_f32_e32 v0, v0
	v_rcp_f32_e32 v11, v11
	v_mul_f32_e32 v13, 0xba38aa3b, v13
	v_exp_f32_e32 v12, v12
	v_exp_f32_e32 v13, v13
	v_fma_f32 v0, v0, s49, 0.5
	v_fma_f32 v11, v11, s49, 0.5
	v_add_f32_e32 v12, 1.0, v12
	v_max_f32_e32 v0, 1.0, v0
	v_max_f32_e32 v11, 1.0, v11
	v_add_f32_e32 v13, 1.0, v13
	v_cvt_u32_f32_e32 v0, v0
	v_cvt_u32_f32_e32 v11, v11
	v_rcp_f32_e32 v12, v12
	v_rcp_f32_e32 v13, v13
	v_mul_f32_e32 v6, 0xba38aa3b, v6
	v_lshl_or_b32 v0, v11, 8, v0
	v_fma_f32 v11, v12, s49, 0.5
	v_fma_f32 v12, v13, s49, 0.5
	v_max_f32_e32 v11, 1.0, v11
	v_max_f32_e32 v12, 1.0, v12
	v_mul_f32_e32 v7, 0xba38aa3b, v7
	v_cvt_u32_f32_sdwa v11, v11 dst_sel:WORD_1 dst_unused:UNUSED_PAD src0_sel:DWORD
	v_cvt_u32_f32_sdwa v12, v12 dst_sel:BYTE_3 dst_unused:UNUSED_PAD src0_sel:DWORD
	v_exp_f32_e32 v6, v6
	v_exp_f32_e32 v7, v7
	s_lshl_b32 s39, s39, 8
	s_add_i32 s39, s40, s39
	v_or3_b32 v11, v0, v11, v12
	v_add_f32_e32 v0, 1.0, v6
	v_add_f32_e32 v6, 1.0, v7
	v_mul_f32_e32 v7, 0xba38aa3b, v8
	v_mul_f32_e32 v8, 0xba38aa3b, v9
	v_mul_f32_e32 v2, 0xba38aa3b, v2
	v_mul_f32_e32 v3, 0xba38aa3b, v3
	v_add_u32_e32 v140, s39, v140
	v_exp_f32_e32 v7, v7
	v_exp_f32_e32 v8, v8
	v_exp_f32_e32 v2, v2
	v_exp_f32_e32 v3, v3
	v_mad_i64_i32 v[140:141], s[44:45], v140, s93, v[132:133]
	v_ashrrev_i32_e32 v143, 31, v142
	v_mul_f32_e32 v4, 0xba38aa3b, v4
	v_mul_f32_e32 v5, 0xba38aa3b, v5
	v_lshl_add_u64 v[126:127], v[140:141], 0, v[142:143]
	v_exp_f32_e32 v4, v4
	v_exp_f32_e32 v5, v5
	v_add_co_u32_e32 v94, vcc, s48, v126
	v_rcp_f32_e32 v0, v0
	s_nop 0
	v_addc_co_u32_e32 v95, vcc, 0, v127, vcc
	v_rcp_f32_e32 v6, v6
	v_add_f32_e32 v7, 1.0, v7
	v_add_f32_e32 v8, 1.0, v8
	v_add_f32_e32 v2, 1.0, v2
	v_add_f32_e32 v3, 1.0, v3
	v_add_co_u32_e32 v78, vcc, s26, v126
	v_rcp_f32_e32 v7, v7
	v_rcp_f32_e32 v8, v8
	v_rcp_f32_e32 v2, v2
	v_rcp_f32_e32 v3, v3
	v_addc_co_u32_e32 v79, vcc, 0, v127, vcc
	s_mov_b32 s38, 0x90000
	v_add_f32_e32 v4, 1.0, v4
	v_add_f32_e32 v5, 1.0, v5
	v_add_co_u32_e32 v62, vcc, s38, v126
	v_rcp_f32_e32 v4, v4
	v_rcp_f32_e32 v5, v5
	v_addc_co_u32_e32 v63, vcc, 0, v127, vcc
	s_mov_b32 s38, 0xc0000
	v_fma_f32 v0, v0, s49, 0.5
	v_fma_f32 v6, v6, s49, 0.5
	v_add_co_u32_e32 v46, vcc, s38, v126
	v_max_f32_e32 v0, 1.0, v0
	v_max_f32_e32 v6, 1.0, v6
	v_fma_f32 v7, v7, s49, 0.5
	v_fma_f32 v8, v8, s49, 0.5
	v_fma_f32 v2, v2, s49, 0.5
	v_fma_f32 v3, v3, s49, 0.5
	v_addc_co_u32_e32 v47, vcc, 0, v127, vcc
	s_mov_b32 s38, 0xf0000
	v_cvt_u32_f32_e32 v0, v0
	v_cvt_u32_f32_e32 v6, v6
	v_max_f32_e32 v7, 1.0, v7
	v_max_f32_e32 v8, 1.0, v8
	v_max_f32_e32 v2, 1.0, v2
	v_max_f32_e32 v3, 1.0, v3
	v_add_co_u32_e32 v30, vcc, s38, v126
	v_cvt_u32_f32_sdwa v7, v7 dst_sel:WORD_1 dst_unused:UNUSED_PAD src0_sel:DWORD
	v_cvt_u32_f32_sdwa v8, v8 dst_sel:BYTE_3 dst_unused:UNUSED_PAD src0_sel:DWORD
	v_cvt_u32_f32_e32 v2, v2
	v_cvt_u32_f32_e32 v3, v3
	v_fma_f32 v4, v4, s49, 0.5
	v_fma_f32 v5, v5, s49, 0.5
	v_addc_co_u32_e32 v31, vcc, 0, v127, vcc
	v_max_f32_e32 v4, 1.0, v4
	v_max_f32_e32 v5, 1.0, v5
	v_add_co_u32_e32 v14, vcc, s27, v126
	v_cvt_u32_f32_sdwa v4, v4 dst_sel:WORD_1 dst_unused:UNUSED_PAD src0_sel:DWORD
	v_cvt_u32_f32_sdwa v5, v5 dst_sel:BYTE_3 dst_unused:UNUSED_PAD src0_sel:DWORD
	v_addc_co_u32_e32 v15, vcc, 0, v127, vcc
	v_lshl_or_b32 v0, v6, 8, v0
	v_or3_b32 v12, v0, v7, v8
	v_lshl_or_b32 v0, v3, 8, v2
	v_add_co_u32_e32 v2, vcc, 0x150000, v126
	v_or3_b32 v13, v0, v4, v5
	s_nop 0
	v_addc_co_u32_e32 v3, vcc, 0, v127, vcc
	s_and_b64 vcc, exec, s[4:5]
	s_mov_b32 s39, s25
	s_mov_b32 s38, s24
	s_mov_b32 s45, s37
	s_mov_b32 s44, s36
	global_store_dwordx4 v[126:127], v[122:125], off
	global_store_dwordx4 v[94:95], v[106:109], off
	global_store_dwordx4 v[78:79], v[90:93], off
	global_store_dwordx4 v[62:63], v[74:77], off
	global_store_dwordx4 v[46:47], v[58:61], off
	global_store_dwordx4 v[30:31], v[42:45], off
	global_store_dwordx4 v[14:15], v[26:29], off
	global_store_dwordx4 v[2:3], v[10:13], off
	s_cbranch_vccz .LBB0_556
	v_readlane_b32 s4, v255, 6
	s_waitcnt vmcnt(0)
	v_readlane_b32 s5, v255, 7
	s_andn2_b64 vcc, exec, s[4:5]
	s_cbranch_vccnz .LBB0_563
	s_barrier

; #define PG8_STAGE(bufoff, gbase, voff) do { unsigned _g = (gbase); asm volatile("" : "+s"(_g));   _Pragma("unroll") for (int _i = 0; _i < 2; ++_i) \
;         __builtin_amdgcn_global_load_lds((const unsigned*)(wsb + (size_t)(unsigned)(_g + (voff)[_i])), (LAS unsigned*)(lds + (bufoff) + ldsw + _i * 8192), 16, 0, 0); } while (0)
; #define PG8_WAIT_V(n) asm volatile("s_waitcnt vmcnt(" #n ")" ::: "memory")
; #define PG8_WAIT_L(n) asm volatile("s_waitcnt lgkmcnt(" #n ")" ::: "memory")
; #define PG8_BAR __builtin_amdgcn_s_barrier()
; #define PG8_SCHED __builtin_amdgcn_sched_barrier(0)
;     ...
;             const unsigned a2 = last ? nA : cA + (unsigned)(t + 2) * kstep, b2 = last ? nB : cB + (unsigned)(t + 2) * kstep;
;             const unsigned a3 = a2 + kstep, b3 = b2 + kstep;
;             if constexpr (SP2) {
;             PG8_LDB(B0, 0, 0); PG8_LDB(B1, 0, 1); PG8_SCHED; PG8_LDA(At, 0, 0); PG8_STAGE(PG8_SA(1, 1), a1 + hstep, voffA);
;             PG8_WAIT_V(8); PG8_WAIT_L(0); PG8_BAR; PG8_MMA(0, 0, At, B0); PG8_MMA(0, 1, At, B1); PG8_BAR; PG8_SCHED;
;             PG8_LDA(At, 0, 1); PG8_STAGE(PG8_SB(0, 0), b2, voffB); PG8_STAGE(PG8_SB(0, 1), b2 + hstep, voffB); PG8_STAGE(PG8_SA(0, 0), a2, voffA);
;             PG8_WAIT_V(8); PG8_WAIT_L(0); PG8_BAR; PG8_MMA(1, 0, At, B0); PG8_MMA(1, 1, At, B1); PG8_BAR; PG8_SCHED;
.LBB0_785:
	v_readfirstlane_b32 s100, v196
	v_readfirstlane_b32 s101, v197
	s_nop 1
	s_sub_u32 s100, s100, 0x10000000
	s_subb_u32 s101, s101, 0
	s_add_i32 s11, s86, s89
	s_add_i32 s8, s11, 0x100
	s_add_i32 s9, s88, s89
	s_cmpk_eq_i32 s89, 0x1f00
	s_cselect_b32 s10, s46, s8
	s_cselect_b32 s9, s47, s9
	s_add_i32 s91, 0, 0x10000
	v_add_u32_e32 v0, s91, v206
	s_add_i32 s96, 0, 0x14000
	ds_read_b128 v[132:135], v0
	ds_read_b128 v[136:139], v0 offset:1024
	ds_read_b128 v[140:143], v0 offset:2048
	ds_read_b128 v[144:147], v0 offset:3072
	v_add_u32_e32 v0, s96, v206
	ds_read_b128 v[148:151], v0
	ds_read_b128 v[152:155], v0 offset:1024
	ds_read_b128 v[156:159], v0 offset:2048
	ds_read_b128 v[160:163], v0 offset:3072
	s_add_i32 s8, s10, 0x80
	s_add_i32 s11, s11, 0x100080
	ds_read_b128 v[164:167], v207
	ds_read_b128 v[168:171], v207 offset:1024
	ds_read_b128 v[172:175], v207 offset:2048
	ds_read_b128 v[176:179], v207 offset:3072
	ds_read_b128 v[180:183], v207 offset:4096
	ds_read_b128 v[184:187], v207 offset:5120
	ds_read_b128 v[188:191], v207 offset:6144
	ds_read_b128 v[192:195], v207 offset:7168
	s_add_i32 m0, s23, 0xc000
	s_add_i32 vcc_lo, s11, 0x10000000
	s_add_u32 vcc_lo, s100, vcc_lo
	s_addc_u32 vcc_hi, s101, 0
	global_load_lds_dwordx4 v202, vcc
	s_add_i32 m0, s23, 0xe000
	s_nop 0
	global_load_lds_dwordx4 v204, vcc
	s_waitcnt vmcnt(8)
	s_waitcnt lgkmcnt(0)
	s_barrier
	s_setprio 1
	s_waitcnt lgkmcnt(0)
	v_mfma_f32_16x16x32_bf16 v[128:131], v[132:135], v[164:167], v[128:131]
	v_mfma_f32_16x16x32_bf16 v[124:127], v[140:143], v[164:167], v[124:127]
	v_mfma_f32_16x16x32_bf16 v[112:115], v[132:135], v[172:175], v[112:115]
	v_mfma_f32_16x16x32_bf16 v[108:111], v[140:143], v[172:175], v[108:111]
	v_mfma_f32_16x16x32_bf16 v[96:99], v[132:135], v[180:183], v[96:99]
	v_mfma_f32_16x16x32_bf16 v[92:95], v[140:143], v[180:183], v[92:95]
	v_mfma_f32_16x16x32_bf16 v[80:83], v[132:135], v[188:191], v[80:83]
	v_mfma_f32_16x16x32_bf16 v[76:79], v[140:143], v[188:191], v[76:79]
	v_mfma_f32_16x16x32_bf16 v[128:131], v[136:139], v[168:171], v[128:131]
	v_mfma_f32_16x16x32_bf16 v[124:127], v[144:147], v[168:171], v[124:127]
	v_mfma_f32_16x16x32_bf16 v[112:115], v[136:139], v[176:179], v[112:115]
	v_mfma_f32_16x16x32_bf16 v[108:111], v[144:147], v[176:179], v[108:111]
	v_mfma_f32_16x16x32_bf16 v[96:99], v[136:139], v[184:187], v[96:99]
	v_mfma_f32_16x16x32_bf16 v[92:95], v[144:147], v[184:187], v[92:95]
	v_mfma_f32_16x16x32_bf16 v[80:83], v[136:139], v[192:195], v[80:83]
	v_mfma_f32_16x16x32_bf16 v[76:79], v[144:147], v[192:195], v[76:79]
	s_setprio 0
	s_setprio 1
	v_mfma_f32_16x16x32_bf16 v[120:123], v[148:151], v[164:167], v[120:123]
	v_mfma_f32_16x16x32_bf16 v[116:119], v[156:159], v[164:167], v[116:119]
	v_mfma_f32_16x16x32_bf16 v[104:107], v[148:151], v[172:175], v[104:107]
	v_mfma_f32_16x16x32_bf16 v[100:103], v[156:159], v[172:175], v[100:103]
	v_mfma_f32_16x16x32_bf16 v[88:91], v[148:151], v[180:183], v[88:91]
	v_mfma_f32_16x16x32_bf16 v[84:87], v[156:159], v[180:183], v[84:87]
	v_mfma_f32_16x16x32_bf16 v[72:75], v[148:151], v[188:191], v[72:75]
	v_mfma_f32_16x16x32_bf16 v[68:71], v[156:159], v[188:191], v[68:71]
	v_mfma_f32_16x16x32_bf16 v[120:123], v[152:155], v[168:171], v[120:123]
	v_mfma_f32_16x16x32_bf16 v[116:119], v[160:163], v[168:171], v[116:119]
	v_mfma_f32_16x16x32_bf16 v[104:107], v[152:155], v[176:179], v[104:107]
	v_mfma_f32_16x16x32_bf16 v[100:103], v[160:163], v[176:179], v[100:103]
	v_mfma_f32_16x16x32_bf16 v[88:91], v[152:155], v[184:187], v[88:91]
	v_mfma_f32_16x16x32_bf16 v[84:87], v[160:163], v[184:187], v[84:87]
	v_mfma_f32_16x16x32_bf16 v[72:75], v[152:155], v[192:195], v[72:75]
	v_mfma_f32_16x16x32_bf16 v[68:71], v[160:163], v[192:195], v[68:71]
	s_setprio 0
	s_barrier
	s_mov_b32 s11, s9
	ds_read_b128 v[164:167], v207 offset:16384
	ds_read_b128 v[168:171], v207 offset:17408
	ds_read_b128 v[172:175], v207 offset:18432
	ds_read_b128 v[176:179], v207 offset:19456
	ds_read_b128 v[180:183], v207 offset:20480
	ds_read_b128 v[184:187], v207 offset:21504
	ds_read_b128 v[188:191], v207 offset:22528
	ds_read_b128 v[192:195], v207 offset:23552
	s_add_i32 s91, s91, s7
	s_add_i32 vcc_lo, s11, 0x10000000
	s_add_u32 vcc_lo, s100, vcc_lo
	s_addc_u32 vcc_hi, s101, 0
	s_mov_b32 m0, s91
	s_nop 0
	global_load_lds_dwordx4 v203, vcc
	s_add_i32 m0, s91, 0x2000
	s_add_i32 s11, s9, 0x100000
	global_load_lds_dwordx4 v205, vcc
	s_add_i32 s91, s96, s7
	s_add_i32 vcc_lo, s11, 0x10000000
	s_add_u32 vcc_lo, s100, vcc_lo
	s_addc_u32 vcc_hi, s101, 0
	s_mov_b32 m0, s91
	s_nop 0
	global_load_lds_dwordx4 v203, vcc
	s_add_i32 m0, s91, 0x2000
	s_mov_b32 s11, s10
	global_load_lds_dwordx4 v205, vcc
	s_mov_b32 m0, s23
	s_add_i32 vcc_lo, s11, 0x10000000
	s_add_u32 vcc_lo, s100, vcc_lo
	s_addc_u32 vcc_hi, s101, 0
	global_load_lds_dwordx4 v202, vcc
	s_mov_b32 m0, s24
	s_nop 0
	global_load_lds_dwordx4 v204, vcc
	s_waitcnt vmcnt(8)
	s_waitcnt lgkmcnt(0)
	s_barrier
; #define PG8_STAGE(bufoff, gbase, voff) do { unsigned _g = (gbase); asm volatile("" : "+s"(_g));   _Pragma("unroll") for (int _i = 0; _i < 2; ++_i) \
;         __builtin_amdgcn_global_load_lds((const unsigned*)(wsb + (size_t)(unsigned)(_g + (voff)[_i])), (LAS unsigned*)(lds + (bufoff) + ldsw + _i * 8192), 16, 0, 0); } while (0)
; #define PG8_WAIT_V(n) asm volatile("s_waitcnt vmcnt(" #n ")" ::: "memory")
; #define PG8_WAIT_L(n) asm volatile("s_waitcnt lgkmcnt(" #n ")" ::: "memory")
; #define PG8_BAR __builtin_amdgcn_s_barrier()
; #define PG8_SCHED __builtin_amdgcn_sched_barrier(0)
;     ...
;             PG8_WAIT_V(8); PG8_WAIT_L(0); PG8_BAR; PG8_MMA(1, 0, At, B0); PG8_MMA(1, 1, At, B1); PG8_BAR; PG8_SCHED;
;             PG8_LDB(B0, 1, 0); PG8_LDB(B1, 1, 1); PG8_SCHED; PG8_LDA(At, 1, 0); PG8_STAGE(PG8_SA(0, 1), a2 + hstep, voffA);
;             PG8_WAIT_V(8); PG8_WAIT_L(0); PG8_BAR; PG8_MMA(0, 0, At, B0); PG8_MMA(0, 1, At, B1); PG8_BAR; PG8_SCHED;
	s_setprio 1
	s_waitcnt lgkmcnt(0)
	v_mfma_f32_16x16x32_bf16 v[64:67], v[132:135], v[164:167], v[64:67]
	v_mfma_f32_16x16x32_bf16 v[60:63], v[140:143], v[164:167], v[60:63]
	v_mfma_f32_16x16x32_bf16 v[48:51], v[132:135], v[172:175], v[48:51]
	v_mfma_f32_16x16x32_bf16 v[44:47], v[140:143], v[172:175], v[44:47]
	v_mfma_f32_16x16x32_bf16 v[32:35], v[132:135], v[180:183], v[32:35]
	v_mfma_f32_16x16x32_bf16 v[28:31], v[140:143], v[180:183], v[28:31]
	v_mfma_f32_16x16x32_bf16 v[16:19], v[132:135], v[188:191], v[16:19]
	v_mfma_f32_16x16x32_bf16 v[12:15], v[140:143], v[188:191], v[12:15]
	v_mfma_f32_16x16x32_bf16 v[64:67], v[136:139], v[168:171], v[64:67]
	v_mfma_f32_16x16x32_bf16 v[60:63], v[144:147], v[168:171], v[60:63]
	v_mfma_f32_16x16x32_bf16 v[48:51], v[136:139], v[176:179], v[48:51]
	v_mfma_f32_16x16x32_bf16 v[44:47], v[144:147], v[176:179], v[44:47]
	v_mfma_f32_16x16x32_bf16 v[32:35], v[136:139], v[184:187], v[32:35]
	v_mfma_f32_16x16x32_bf16 v[28:31], v[144:147], v[184:187], v[28:31]
	v_mfma_f32_16x16x32_bf16 v[16:19], v[136:139], v[192:195], v[16:19]
	v_mfma_f32_16x16x32_bf16 v[12:15], v[144:147], v[192:195], v[12:15]
	s_setprio 0
	s_setprio 1
	v_mfma_f32_16x16x32_bf16 v[56:59], v[148:151], v[164:167], v[56:59]
	v_mfma_f32_16x16x32_bf16 v[52:55], v[156:159], v[164:167], v[52:55]
	v_mfma_f32_16x16x32_bf16 v[40:43], v[148:151], v[172:175], v[40:43]
	v_mfma_f32_16x16x32_bf16 v[36:39], v[156:159], v[172:175], v[36:39]
	v_mfma_f32_16x16x32_bf16 v[24:27], v[148:151], v[180:183], v[24:27]
	v_mfma_f32_16x16x32_bf16 v[20:23], v[156:159], v[180:183], v[20:23]
	v_mfma_f32_16x16x32_bf16 v[8:11], v[148:151], v[188:191], v[8:11]
	v_mfma_f32_16x16x32_bf16 v[2:5], v[156:159], v[188:191], v[4:7]
	v_mfma_f32_16x16x32_bf16 v[56:59], v[152:155], v[168:171], v[56:59]
	v_mfma_f32_16x16x32_bf16 v[52:55], v[160:163], v[168:171], v[52:55]
	v_mfma_f32_16x16x32_bf16 v[40:43], v[152:155], v[176:179], v[40:43]
	v_mfma_f32_16x16x32_bf16 v[36:39], v[160:163], v[176:179], v[36:39]
	v_mfma_f32_16x16x32_bf16 v[24:27], v[152:155], v[184:187], v[24:27]
	v_mfma_f32_16x16x32_bf16 v[20:23], v[160:163], v[184:187], v[20:23]
	v_mfma_f32_16x16x32_bf16 v[8:11], v[152:155], v[192:195], v[8:11]
	v_mfma_f32_16x16x32_bf16 v[2:5], v[160:163], v[192:195], v[2:5]
	s_setprio 0
	s_barrier
	s_add_i32 s11, 0, 0x18000
	v_add_u32_e32 v0, s11, v206
	s_add_i32 s91, 0, 0x1c000
	ds_read_b128 v[132:135], v0
	ds_read_b128 v[136:139], v0 offset:1024
	ds_read_b128 v[140:143], v0 offset:2048
	ds_read_b128 v[144:147], v0 offset:3072
	v_add_u32_e32 v0, s91, v206
	ds_read_b128 v[148:151], v0
	ds_read_b128 v[152:155], v0 offset:1024
	ds_read_b128 v[156:159], v0 offset:2048
	ds_read_b128 v[160:163], v0 offset:3072
	s_add_i32 s10, s10, 0x100000
	ds_read_b128 v[164:167], v207 offset:32768
	ds_read_b128 v[168:171], v207 offset:33792
	ds_read_b128 v[172:175], v207 offset:34816
	ds_read_b128 v[176:179], v207 offset:35840
	ds_read_b128 v[180:183], v207 offset:36864
	ds_read_b128 v[184:187], v207 offset:37888
	ds_read_b128 v[188:191], v207 offset:38912
	ds_read_b128 v[192:195], v207 offset:39936
	s_mov_b32 m0, s25
	s_add_i32 vcc_lo, s10, 0x10000000
	s_add_u32 vcc_lo, s100, vcc_lo
	s_addc_u32 vcc_hi, s101, 0
	global_load_lds_dwordx4 v202, vcc
	s_mov_b32 m0, s38
	s_nop 0
	global_load_lds_dwordx4 v204, vcc
	s_waitcnt vmcnt(8)
	s_waitcnt lgkmcnt(0)
	s_barrier
	s_setprio 1
	s_waitcnt lgkmcnt(0)
	v_mfma_f32_16x16x32_bf16 v[128:131], v[132:135], v[164:167], v[128:131]
	v_mfma_f32_16x16x32_bf16 v[124:127], v[140:143], v[164:167], v[124:127]
	v_mfma_f32_16x16x32_bf16 v[112:115], v[132:135], v[172:175], v[112:115]
	v_mfma_f32_16x16x32_bf16 v[108:111], v[140:143], v[172:175], v[108:111]
	v_mfma_f32_16x16x32_bf16 v[96:99], v[132:135], v[180:183], v[96:99]
	v_mfma_f32_16x16x32_bf16 v[92:95], v[140:143], v[180:183], v[92:95]
	v_mfma_f32_16x16x32_bf16 v[80:83], v[132:135], v[188:191], v[80:83]
	v_mfma_f32_16x16x32_bf16 v[76:79], v[140:143], v[188:191], v[76:79]
	v_mfma_f32_16x16x32_bf16 v[128:131], v[136:139], v[168:171], v[128:131]
	v_mfma_f32_16x16x32_bf16 v[124:127], v[144:147], v[168:171], v[124:127]
	v_mfma_f32_16x16x32_bf16 v[112:115], v[136:139], v[176:179], v[112:115]
	v_mfma_f32_16x16x32_bf16 v[108:111], v[144:147], v[176:179], v[108:111]
	v_mfma_f32_16x16x32_bf16 v[96:99], v[136:139], v[184:187], v[96:99]
	v_mfma_f32_16x16x32_bf16 v[92:95], v[144:147], v[184:187], v[92:95]
	v_mfma_f32_16x16x32_bf16 v[80:83], v[136:139], v[192:195], v[80:83]
	v_mfma_f32_16x16x32_bf16 v[76:79], v[144:147], v[192:195], v[76:79]
	s_setprio 0
	s_setprio 1
	v_mfma_f32_16x16x32_bf16 v[120:123], v[148:151], v[164:167], v[120:123]
	v_mfma_f32_16x16x32_bf16 v[116:119], v[156:159], v[164:167], v[116:119]
	v_mfma_f32_16x16x32_bf16 v[104:107], v[148:151], v[172:175], v[104:107]
	v_mfma_f32_16x16x32_bf16 v[100:103], v[156:159], v[172:175], v[100:103]
	v_mfma_f32_16x16x32_bf16 v[88:91], v[148:151], v[180:183], v[88:91]
	v_mfma_f32_16x16x32_bf16 v[84:87], v[156:159], v[180:183], v[84:87]
	v_mfma_f32_16x16x32_bf16 v[72:75], v[148:151], v[188:191], v[72:75]
	v_mfma_f32_16x16x32_bf16 v[68:71], v[156:159], v[188:191], v[68:71]
	v_mfma_f32_16x16x32_bf16 v[120:123], v[152:155], v[168:171], v[120:123]
	v_mfma_f32_16x16x32_bf16 v[116:119], v[160:163], v[168:171], v[116:119]
	v_mfma_f32_16x16x32_bf16 v[104:107], v[152:155], v[176:179], v[104:107]
	v_mfma_f32_16x16x32_bf16 v[100:103], v[160:163], v[176:179], v[100:103]
	v_mfma_f32_16x16x32_bf16 v[88:91], v[152:155], v[184:187], v[88:91]
	v_mfma_f32_16x16x32_bf16 v[84:87], v[160:163], v[184:187], v[84:87]
	v_mfma_f32_16x16x32_bf16 v[72:75], v[152:155], v[192:195], v[72:75]
	v_mfma_f32_16x16x32_bf16 v[68:71], v[160:163], v[192:195], v[68:71]
	s_setprio 0
	s_barrier
; __device__ __forceinline__ int lane_id_hw() { int l; asm volatile("v_mbcnt_lo_u32_b32 %0, -1, 0\n\tv_mbcnt_hi_u32_b32 %0, -1, %0" : "=v"(l)); return l; }
; #define PG8_STAGE(bufoff, gbase, voff) do { unsigned _g = (gbase); asm volatile("" : "+s"(_g));   _Pragma("unroll") for (int _i = 0; _i < 2; ++_i) \
;         __builtin_amdgcn_global_load_lds((const unsigned*)(wsb + (size_t)(unsigned)(_g + (voff)[_i])), (LAS unsigned*)(lds + (bufoff) + ldsw + _i * 8192), 16, 0, 0); } while (0)
; #define PG8_WAIT_V(n) asm volatile("s_waitcnt vmcnt(" #n ")" ::: "memory")
; #define PG8_WAIT_L(n) asm volatile("s_waitcnt lgkmcnt(" #n ")" ::: "memory")
; #define PG8_BAR __builtin_amdgcn_s_barrier()
; #define PG8_SCHED __builtin_amdgcn_sched_barrier(0)
;     ...
;         for (int t = 0; t < nt; t += 2) {
;             if constexpr (Epi::HAS_MID) { if (t == Epi::MID0 || t == Epi::MID1) { const int l2 = lane_id_hw(); E.mid(acc, cur, t == Epi::MID0 ? 0 : 1, wr, wc, l2 & 15, l2 >> 4); } }
;     ...
;             PG8_LDA(At, 1, 1); PG8_STAGE(PG8_SB(1, 0), b3, voffB); PG8_STAGE(PG8_SB(1, 1), b3 + hstep, voffB); PG8_STAGE(PG8_SA(1, 0), a3, voffA);
;             PG8_WAIT_V(8); PG8_WAIT_L(0); PG8_BAR; PG8_MMA(1, 0, At, B0); PG8_MMA(1, 1, At, B1); PG8_BAR; PG8_SCHED;
	s_add_i32 s10, s9, 0x80
	ds_read_b128 v[164:167], v207 offset:49152
	ds_read_b128 v[168:171], v207 offset:50176
	ds_read_b128 v[172:175], v207 offset:51200
	ds_read_b128 v[176:179], v207 offset:52224
	ds_read_b128 v[180:183], v207 offset:53248
	ds_read_b128 v[184:187], v207 offset:54272
	ds_read_b128 v[188:191], v207 offset:55296
	ds_read_b128 v[192:195], v207 offset:56320
	s_add_i32 s11, s11, s7
	s_add_i32 vcc_lo, s10, 0x10000000
	s_add_u32 vcc_lo, s100, vcc_lo
	s_addc_u32 vcc_hi, s101, 0
	s_mov_b32 m0, s11
	s_nop 0
	global_load_lds_dwordx4 v203, vcc
	s_add_i32 m0, s11, 0x2000
	s_add_i32 s9, s9, 0x100080
	global_load_lds_dwordx4 v205, vcc
	s_add_i32 s10, s91, s7
	s_add_i32 vcc_lo, s9, 0x10000000
	s_add_u32 vcc_lo, s100, vcc_lo
	s_addc_u32 vcc_hi, s101, 0
	s_mov_b32 m0, s10
	s_nop 0
	global_load_lds_dwordx4 v203, vcc
	s_add_i32 m0, s10, 0x2000
	s_nop 0
	global_load_lds_dwordx4 v205, vcc
	s_mov_b32 m0, s39
	s_add_i32 vcc_lo, s8, 0x10000000
	s_add_u32 vcc_lo, s100, vcc_lo
	s_addc_u32 vcc_hi, s101, 0
	global_load_lds_dwordx4 v202, vcc
	s_mov_b32 m0, s44
	s_nop 0
	global_load_lds_dwordx4 v204, vcc
	s_waitcnt vmcnt(8)
	s_waitcnt lgkmcnt(0)
	s_barrier
	s_setprio 1
	s_waitcnt lgkmcnt(0)
	v_mfma_f32_16x16x32_bf16 v[64:67], v[132:135], v[164:167], v[64:67]
	v_mfma_f32_16x16x32_bf16 v[60:63], v[140:143], v[164:167], v[60:63]
	v_mfma_f32_16x16x32_bf16 v[48:51], v[132:135], v[172:175], v[48:51]
	v_mfma_f32_16x16x32_bf16 v[44:47], v[140:143], v[172:175], v[44:47]
	v_mfma_f32_16x16x32_bf16 v[32:35], v[132:135], v[180:183], v[32:35]
	v_mfma_f32_16x16x32_bf16 v[28:31], v[140:143], v[180:183], v[28:31]
	v_mfma_f32_16x16x32_bf16 v[16:19], v[132:135], v[188:191], v[16:19]
	v_mfma_f32_16x16x32_bf16 v[12:15], v[140:143], v[188:191], v[12:15]
	v_mfma_f32_16x16x32_bf16 v[64:67], v[136:139], v[168:171], v[64:67]
	v_mfma_f32_16x16x32_bf16 v[60:63], v[144:147], v[168:171], v[60:63]
	v_mfma_f32_16x16x32_bf16 v[48:51], v[136:139], v[176:179], v[48:51]
	v_mfma_f32_16x16x32_bf16 v[44:47], v[144:147], v[176:179], v[44:47]
	v_mfma_f32_16x16x32_bf16 v[32:35], v[136:139], v[184:187], v[32:35]
	v_mfma_f32_16x16x32_bf16 v[28:31], v[144:147], v[184:187], v[28:31]
	v_mfma_f32_16x16x32_bf16 v[16:19], v[136:139], v[192:195], v[16:19]
	v_mfma_f32_16x16x32_bf16 v[12:15], v[144:147], v[192:195], v[12:15]
	s_setprio 0
	s_setprio 1
	v_mfma_f32_16x16x32_bf16 v[56:59], v[148:151], v[164:167], v[56:59]
	v_mfma_f32_16x16x32_bf16 v[52:55], v[156:159], v[164:167], v[52:55]
	v_mfma_f32_16x16x32_bf16 v[40:43], v[148:151], v[172:175], v[40:43]
	v_mfma_f32_16x16x32_bf16 v[36:39], v[156:159], v[172:175], v[36:39]
	v_mfma_f32_16x16x32_bf16 v[24:27], v[148:151], v[180:183], v[24:27]
	v_mfma_f32_16x16x32_bf16 v[20:23], v[156:159], v[180:183], v[20:23]
	v_mfma_f32_16x16x32_bf16 v[6:9], v[148:151], v[188:191], v[8:11]
	v_mfma_f32_16x16x32_bf16 v[2:5], v[156:159], v[188:191], v[2:5]
	v_mfma_f32_16x16x32_bf16 v[56:59], v[152:155], v[168:171], v[56:59]
	v_mfma_f32_16x16x32_bf16 v[52:55], v[160:163], v[168:171], v[52:55]
	v_mfma_f32_16x16x32_bf16 v[40:43], v[152:155], v[176:179], v[40:43]
	v_mfma_f32_16x16x32_bf16 v[36:39], v[160:163], v[176:179], v[36:39]
	v_mfma_f32_16x16x32_bf16 v[24:27], v[152:155], v[184:187], v[24:27]
	v_mfma_f32_16x16x32_bf16 v[20:23], v[160:163], v[184:187], v[20:23]
	v_mfma_f32_16x16x32_bf16 v[8:11], v[152:155], v[192:195], v[6:9]
	v_mfma_f32_16x16x32_bf16 v[4:7], v[160:163], v[192:195], v[2:5]
	s_setprio 0
	s_barrier
	s_add_i32 s8, s90, 2
	s_addk_i32 s89, 0x100
	s_cmp_gt_u32 s90, 61
	s_cbranch_scc1 .LBB0_777
	s_mov_b32 s90, s8
	s_cmp_lt_i32 s90, 48
	s_cbranch_scc1 .LBB0_781

; #define PG8_STAGE(bufoff, gbase, voff) do { unsigned _g = (gbase); asm volatile("" : "+s"(_g));   _Pragma("unroll") for (int _i = 0; _i < 2; ++_i) \
;         __builtin_amdgcn_global_load_lds((const unsigned*)(wsb + (size_t)(unsigned)(_g + (voff)[_i])), (LAS unsigned*)(lds + (bufoff) + ldsw + _i * 8192), 16, 0, 0); } while (0)
; #define PG8_WAIT_V(n) asm volatile("s_waitcnt vmcnt(" #n ")" ::: "memory")
; #define PG8_WAIT_L(n) asm volatile("s_waitcnt lgkmcnt(" #n ")" ::: "memory")
; #define PG8_BAR __builtin_amdgcn_s_barrier()
; #define PG8_SCHED __builtin_amdgcn_sched_barrier(0)
;     ...
;             const unsigned a2 = last ? nA : cA + (unsigned)(t + 2) * kstep, b2 = last ? nB : cB + (unsigned)(t + 2) * kstep;
;             const unsigned a3 = a2 + kstep, b3 = b2 + kstep;
;             if constexpr (SP2) {
;             PG8_LDB(B0, 0, 0); PG8_LDB(B1, 0, 1); PG8_SCHED; PG8_LDA(At, 0, 0); PG8_STAGE(PG8_SA(1, 1), a1 + hstep, voffA);
;             PG8_WAIT_V(8); PG8_WAIT_L(0); PG8_BAR; PG8_MMA(0, 0, At, B0); PG8_MMA(0, 1, At, B1); PG8_BAR; PG8_SCHED;
;             PG8_LDA(At, 0, 1); PG8_STAGE(PG8_SB(0, 0), b2, voffB); PG8_STAGE(PG8_SB(0, 1), b2 + hstep, voffB); PG8_STAGE(PG8_SA(0, 0), a2, voffA);
;             PG8_WAIT_V(8); PG8_WAIT_L(0); PG8_BAR; PG8_MMA(1, 0, At, B0); PG8_MMA(1, 1, At, B1); PG8_BAR; PG8_SCHED;
.LBB0_862:
	v_readfirstlane_b32 s100, v130
	v_readfirstlane_b32 s101, v131
	s_nop 1
	s_sub_u32 s100, s100, 0x10000000
	s_subb_u32 s101, s101, 0
	s_add_i32 s47, s10, 0xfff00080
	s_cmp_eq_u32 s18, 60
	s_cselect_b32 s83, s45, s47
	s_cselect_b32 s82, s46, s11
	s_add_i32 s84, 0, 0x10000
	s_waitcnt lgkmcnt(0)
	v_add_u32_e32 v0, s84, v144
	s_add_i32 s86, 0, 0x14000
	ds_read_b128 v[136:139], v0
	ds_read_b128 v[146:149], v0 offset:1024
	ds_read_b128 v[150:153], v0 offset:2048
	ds_read_b128 v[154:157], v0 offset:3072
	v_add_u32_e32 v0, s86, v144
	ds_read_b128 v[158:161], v0
	ds_read_b128 v[162:165], v0 offset:1024
	ds_read_b128 v[166:169], v0 offset:2048
	ds_read_b128 v[170:173], v0 offset:3072
	s_add_i32 s47, s83, 0x80
	s_mov_b32 s87, s10
	ds_read_b128 v[174:177], v145
	ds_read_b128 v[178:181], v145 offset:1024
	ds_read_b128 v[182:185], v145 offset:2048
	ds_read_b128 v[186:189], v145 offset:3072
	ds_read_b128 v[190:193], v145 offset:4096
	ds_read_b128 v[194:197], v145 offset:5120
	ds_read_b128 v[198:201], v145 offset:6144
	ds_read_b128 v[202:205], v145 offset:7168
	s_add_i32 m0, s22, 0xc000
	s_add_i32 vcc_lo, s87, 0x10000000
	s_add_u32 vcc_lo, s100, vcc_lo
	s_addc_u32 vcc_hi, s101, 0
	global_load_lds_dwordx4 v140, vcc
	s_add_i32 m0, s22, 0xe000
	s_nop 0
	global_load_lds_dwordx4 v142, vcc
	s_waitcnt vmcnt(8)
	s_waitcnt lgkmcnt(0)
	s_barrier
	s_setprio 1
	s_waitcnt lgkmcnt(0)
	v_mfma_f32_16x16x32_bf16 v[126:129], v[136:139], v[174:177], v[126:129]
	v_mfma_f32_16x16x32_bf16 v[122:125], v[150:153], v[174:177], v[122:125]
	v_mfma_f32_16x16x32_bf16 v[110:113], v[136:139], v[182:185], v[110:113]
	v_mfma_f32_16x16x32_bf16 v[106:109], v[150:153], v[182:185], v[106:109]
	v_mfma_f32_16x16x32_bf16 v[94:97], v[136:139], v[190:193], v[94:97]
	v_mfma_f32_16x16x32_bf16 v[90:93], v[150:153], v[190:193], v[90:93]
	v_mfma_f32_16x16x32_bf16 v[78:81], v[136:139], v[198:201], v[78:81]
	v_mfma_f32_16x16x32_bf16 v[74:77], v[150:153], v[198:201], v[74:77]
	v_mfma_f32_16x16x32_bf16 v[126:129], v[146:149], v[178:181], v[126:129]
	v_mfma_f32_16x16x32_bf16 v[122:125], v[154:157], v[178:181], v[122:125]
	v_mfma_f32_16x16x32_bf16 v[110:113], v[146:149], v[186:189], v[110:113]
	v_mfma_f32_16x16x32_bf16 v[106:109], v[154:157], v[186:189], v[106:109]
	v_mfma_f32_16x16x32_bf16 v[94:97], v[146:149], v[194:197], v[94:97]
	v_mfma_f32_16x16x32_bf16 v[90:93], v[154:157], v[194:197], v[90:93]
	v_mfma_f32_16x16x32_bf16 v[78:81], v[146:149], v[202:205], v[78:81]
	v_mfma_f32_16x16x32_bf16 v[74:77], v[154:157], v[202:205], v[74:77]
	s_setprio 0
	s_setprio 1
	v_mfma_f32_16x16x32_bf16 v[118:121], v[158:161], v[174:177], v[118:121]
	v_mfma_f32_16x16x32_bf16 v[114:117], v[166:169], v[174:177], v[114:117]
	v_mfma_f32_16x16x32_bf16 v[102:105], v[158:161], v[182:185], v[102:105]
	v_mfma_f32_16x16x32_bf16 v[98:101], v[166:169], v[182:185], v[98:101]
	v_mfma_f32_16x16x32_bf16 v[86:89], v[158:161], v[190:193], v[86:89]
	v_mfma_f32_16x16x32_bf16 v[82:85], v[166:169], v[190:193], v[82:85]
	v_mfma_f32_16x16x32_bf16 v[70:73], v[158:161], v[198:201], v[70:73]
	v_mfma_f32_16x16x32_bf16 v[66:69], v[166:169], v[198:201], v[66:69]
	v_mfma_f32_16x16x32_bf16 v[118:121], v[162:165], v[178:181], v[118:121]
	v_mfma_f32_16x16x32_bf16 v[114:117], v[170:173], v[178:181], v[114:117]
	v_mfma_f32_16x16x32_bf16 v[102:105], v[162:165], v[186:189], v[102:105]
	v_mfma_f32_16x16x32_bf16 v[98:101], v[170:173], v[186:189], v[98:101]
	v_mfma_f32_16x16x32_bf16 v[86:89], v[162:165], v[194:197], v[86:89]
	v_mfma_f32_16x16x32_bf16 v[82:85], v[170:173], v[194:197], v[82:85]
	v_mfma_f32_16x16x32_bf16 v[70:73], v[162:165], v[202:205], v[70:73]
	v_mfma_f32_16x16x32_bf16 v[66:69], v[170:173], v[202:205], v[66:69]
	s_setprio 0
	s_barrier
	s_mov_b32 s87, s82
	ds_read_b128 v[174:177], v145 offset:16384
	ds_read_b128 v[178:181], v145 offset:17408
	ds_read_b128 v[182:185], v145 offset:18432
	ds_read_b128 v[186:189], v145 offset:19456
	ds_read_b128 v[190:193], v145 offset:20480
	ds_read_b128 v[194:197], v145 offset:21504
	ds_read_b128 v[198:201], v145 offset:22528
	ds_read_b128 v[202:205], v145 offset:23552
	s_add_i32 s84, s84, s7
	s_add_i32 vcc_lo, s87, 0x10000000
	s_add_u32 vcc_lo, s100, vcc_lo
	s_addc_u32 vcc_hi, s101, 0
	s_mov_b32 m0, s84
	s_nop 0
	global_load_lds_dwordx4 v141, vcc
	s_add_i32 m0, s84, 0x2000
	s_add_i32 s84, s82, 0x100000
	global_load_lds_dwordx4 v143, vcc
	s_add_i32 s86, s86, s7
	s_add_i32 vcc_lo, s84, 0x10000000
	s_add_u32 vcc_lo, s100, vcc_lo
	s_addc_u32 vcc_hi, s101, 0
	s_mov_b32 m0, s86
	s_nop 0
	global_load_lds_dwordx4 v141, vcc
	s_add_i32 m0, s86, 0x2000
	s_mov_b32 s84, s83
	global_load_lds_dwordx4 v143, vcc
	s_mov_b32 m0, s22
	s_add_i32 vcc_lo, s84, 0x10000000
	s_add_u32 vcc_lo, s100, vcc_lo
	s_addc_u32 vcc_hi, s101, 0
	global_load_lds_dwordx4 v140, vcc
	s_mov_b32 m0, s23
	s_nop 0
	global_load_lds_dwordx4 v142, vcc
	s_waitcnt vmcnt(8)
	s_waitcnt lgkmcnt(0)
	s_barrier
; #define PG8_STAGE(bufoff, gbase, voff) do { unsigned _g = (gbase); asm volatile("" : "+s"(_g));   _Pragma("unroll") for (int _i = 0; _i < 2; ++_i) \
;         __builtin_amdgcn_global_load_lds((const unsigned*)(wsb + (size_t)(unsigned)(_g + (voff)[_i])), (LAS unsigned*)(lds + (bufoff) + ldsw + _i * 8192), 16, 0, 0); } while (0)
; #define PG8_WAIT_V(n) asm volatile("s_waitcnt vmcnt(" #n ")" ::: "memory")
; #define PG8_WAIT_L(n) asm volatile("s_waitcnt lgkmcnt(" #n ")" ::: "memory")
; #define PG8_BAR __builtin_amdgcn_s_barrier()
; #define PG8_SCHED __builtin_amdgcn_sched_barrier(0)
;     ...
;             PG8_WAIT_V(8); PG8_WAIT_L(0); PG8_BAR; PG8_MMA(1, 0, At, B0); PG8_MMA(1, 1, At, B1); PG8_BAR; PG8_SCHED;
;             PG8_LDB(B0, 1, 0); PG8_LDB(B1, 1, 1); PG8_SCHED; PG8_LDA(At, 1, 0); PG8_STAGE(PG8_SA(0, 1), a2 + hstep, voffA);
;             PG8_WAIT_V(8); PG8_WAIT_L(0); PG8_BAR; PG8_MMA(0, 0, At, B0); PG8_MMA(0, 1, At, B1); PG8_BAR; PG8_SCHED;
	s_setprio 1
	s_waitcnt lgkmcnt(0)
	v_mfma_f32_16x16x32_bf16 v[62:65], v[136:139], v[174:177], v[62:65]
	v_mfma_f32_16x16x32_bf16 v[58:61], v[150:153], v[174:177], v[58:61]
	v_mfma_f32_16x16x32_bf16 v[46:49], v[136:139], v[182:185], v[46:49]
	v_mfma_f32_16x16x32_bf16 v[42:45], v[150:153], v[182:185], v[42:45]
	v_mfma_f32_16x16x32_bf16 v[30:33], v[136:139], v[190:193], v[30:33]
	v_mfma_f32_16x16x32_bf16 v[26:29], v[150:153], v[190:193], v[26:29]
	v_mfma_f32_16x16x32_bf16 v[14:17], v[136:139], v[198:201], v[14:17]
	v_mfma_f32_16x16x32_bf16 v[10:13], v[150:153], v[198:201], v[10:13]
	v_mfma_f32_16x16x32_bf16 v[62:65], v[146:149], v[178:181], v[62:65]
	v_mfma_f32_16x16x32_bf16 v[58:61], v[154:157], v[178:181], v[58:61]
	v_mfma_f32_16x16x32_bf16 v[46:49], v[146:149], v[186:189], v[46:49]
	v_mfma_f32_16x16x32_bf16 v[42:45], v[154:157], v[186:189], v[42:45]
	v_mfma_f32_16x16x32_bf16 v[30:33], v[146:149], v[194:197], v[30:33]
	v_mfma_f32_16x16x32_bf16 v[26:29], v[154:157], v[194:197], v[26:29]
	v_mfma_f32_16x16x32_bf16 v[14:17], v[146:149], v[202:205], v[14:17]
	v_mfma_f32_16x16x32_bf16 v[10:13], v[154:157], v[202:205], v[10:13]
	s_setprio 0
	s_setprio 1
	v_mfma_f32_16x16x32_bf16 v[54:57], v[158:161], v[174:177], v[54:57]
	v_mfma_f32_16x16x32_bf16 v[50:53], v[166:169], v[174:177], v[50:53]
	v_mfma_f32_16x16x32_bf16 v[38:41], v[158:161], v[182:185], v[38:41]
	v_mfma_f32_16x16x32_bf16 v[34:37], v[166:169], v[182:185], v[34:37]
	v_mfma_f32_16x16x32_bf16 v[22:25], v[158:161], v[190:193], v[22:25]
	v_mfma_f32_16x16x32_bf16 v[18:21], v[166:169], v[190:193], v[18:21]
	v_mfma_f32_16x16x32_bf16 v[6:9], v[158:161], v[198:201], v[6:9]
	v_mfma_f32_16x16x32_bf16 v[2:5], v[166:169], v[198:201], v[2:5]
	v_mfma_f32_16x16x32_bf16 v[54:57], v[162:165], v[178:181], v[54:57]
	v_mfma_f32_16x16x32_bf16 v[50:53], v[170:173], v[178:181], v[50:53]
	v_mfma_f32_16x16x32_bf16 v[38:41], v[162:165], v[186:189], v[38:41]
	v_mfma_f32_16x16x32_bf16 v[34:37], v[170:173], v[186:189], v[34:37]
	v_mfma_f32_16x16x32_bf16 v[22:25], v[162:165], v[194:197], v[22:25]
	v_mfma_f32_16x16x32_bf16 v[18:21], v[170:173], v[194:197], v[18:21]
	v_mfma_f32_16x16x32_bf16 v[6:9], v[162:165], v[202:205], v[6:9]
	v_mfma_f32_16x16x32_bf16 v[2:5], v[170:173], v[202:205], v[2:5]
	s_setprio 0
	s_barrier
	s_add_i32 s84, 0, 0x18000
	v_add_u32_e32 v0, s84, v144
	s_add_i32 s86, 0, 0x1c000
	ds_read_b128 v[136:139], v0
	ds_read_b128 v[146:149], v0 offset:1024
	ds_read_b128 v[150:153], v0 offset:2048
	ds_read_b128 v[154:157], v0 offset:3072
	v_add_u32_e32 v0, s86, v144
	ds_read_b128 v[158:161], v0
	ds_read_b128 v[162:165], v0 offset:1024
	ds_read_b128 v[166:169], v0 offset:2048
	ds_read_b128 v[170:173], v0 offset:3072
	s_add_i32 s83, s83, 0x100000
	ds_read_b128 v[174:177], v145 offset:32768
	ds_read_b128 v[178:181], v145 offset:33792
	ds_read_b128 v[182:185], v145 offset:34816
	ds_read_b128 v[186:189], v145 offset:35840
	ds_read_b128 v[190:193], v145 offset:36864
	ds_read_b128 v[194:197], v145 offset:37888
	ds_read_b128 v[198:201], v145 offset:38912
	ds_read_b128 v[202:205], v145 offset:39936
	s_mov_b32 m0, s24
	s_add_i32 vcc_lo, s83, 0x10000000
	s_add_u32 vcc_lo, s100, vcc_lo
	s_addc_u32 vcc_hi, s101, 0
	global_load_lds_dwordx4 v140, vcc
	s_mov_b32 m0, s25
	s_nop 0
	global_load_lds_dwordx4 v142, vcc
	s_waitcnt vmcnt(8)
	s_waitcnt lgkmcnt(0)
	s_barrier
	s_setprio 1
	s_waitcnt lgkmcnt(0)
	v_mfma_f32_16x16x32_bf16 v[126:129], v[136:139], v[174:177], v[126:129]
	v_mfma_f32_16x16x32_bf16 v[122:125], v[150:153], v[174:177], v[122:125]
	v_mfma_f32_16x16x32_bf16 v[110:113], v[136:139], v[182:185], v[110:113]
	v_mfma_f32_16x16x32_bf16 v[106:109], v[150:153], v[182:185], v[106:109]
	v_mfma_f32_16x16x32_bf16 v[94:97], v[136:139], v[190:193], v[94:97]
	v_mfma_f32_16x16x32_bf16 v[90:93], v[150:153], v[190:193], v[90:93]
	v_mfma_f32_16x16x32_bf16 v[78:81], v[136:139], v[198:201], v[78:81]
	v_mfma_f32_16x16x32_bf16 v[74:77], v[150:153], v[198:201], v[74:77]
	v_mfma_f32_16x16x32_bf16 v[126:129], v[146:149], v[178:181], v[126:129]
	v_mfma_f32_16x16x32_bf16 v[122:125], v[154:157], v[178:181], v[122:125]
	v_mfma_f32_16x16x32_bf16 v[110:113], v[146:149], v[186:189], v[110:113]
	v_mfma_f32_16x16x32_bf16 v[106:109], v[154:157], v[186:189], v[106:109]
	v_mfma_f32_16x16x32_bf16 v[94:97], v[146:149], v[194:197], v[94:97]
	v_mfma_f32_16x16x32_bf16 v[90:93], v[154:157], v[194:197], v[90:93]
	v_mfma_f32_16x16x32_bf16 v[78:81], v[146:149], v[202:205], v[78:81]
	v_mfma_f32_16x16x32_bf16 v[74:77], v[154:157], v[202:205], v[74:77]
	s_setprio 0
	s_setprio 1
	v_mfma_f32_16x16x32_bf16 v[118:121], v[158:161], v[174:177], v[118:121]
	v_mfma_f32_16x16x32_bf16 v[114:117], v[166:169], v[174:177], v[114:117]
	v_mfma_f32_16x16x32_bf16 v[102:105], v[158:161], v[182:185], v[102:105]
	v_mfma_f32_16x16x32_bf16 v[98:101], v[166:169], v[182:185], v[98:101]
	v_mfma_f32_16x16x32_bf16 v[86:89], v[158:161], v[190:193], v[86:89]
	v_mfma_f32_16x16x32_bf16 v[82:85], v[166:169], v[190:193], v[82:85]
	v_mfma_f32_16x16x32_bf16 v[70:73], v[158:161], v[198:201], v[70:73]
	v_mfma_f32_16x16x32_bf16 v[66:69], v[166:169], v[198:201], v[66:69]
	v_mfma_f32_16x16x32_bf16 v[118:121], v[162:165], v[178:181], v[118:121]
	v_mfma_f32_16x16x32_bf16 v[114:117], v[170:173], v[178:181], v[114:117]
	v_mfma_f32_16x16x32_bf16 v[102:105], v[162:165], v[186:189], v[102:105]
	v_mfma_f32_16x16x32_bf16 v[98:101], v[170:173], v[186:189], v[98:101]
	v_mfma_f32_16x16x32_bf16 v[86:89], v[162:165], v[194:197], v[86:89]
	v_mfma_f32_16x16x32_bf16 v[82:85], v[170:173], v[194:197], v[82:85]
	v_mfma_f32_16x16x32_bf16 v[70:73], v[162:165], v[202:205], v[70:73]
	v_mfma_f32_16x16x32_bf16 v[66:69], v[170:173], v[202:205], v[66:69]
	s_setprio 0
	s_barrier
; #define GAS __attribute__((address_space(1)))
; __device__ __forceinline__ unsigned cvt_pk_bf16(float lo, float hi) { const f32x2_t_ v = {lo, hi}; const bf16x2_t_ b = __builtin_convertvector(v, bf16x2_t_); return __builtin_bit_cast(unsigned, b); }
; #define PG8_STAGE(bufoff, gbase, voff) do { unsigned _g = (gbase); asm volatile("" : "+s"(_g));   _Pragma("unroll") for (int _i = 0; _i < 2; ++_i) \
;         __builtin_amdgcn_global_load_lds((const unsigned*)(wsb + (size_t)(unsigned)(_g + (voff)[_i])), (LAS unsigned*)(lds + (bufoff) + ldsw + _i * 8192), 16, 0, 0); } while (0)
; #define PG8_WAIT_V(n) asm volatile("s_waitcnt vmcnt(" #n ")" ::: "memory")
; #define PG8_WAIT_L(n) asm volatile("s_waitcnt lgkmcnt(" #n ")" ::: "memory")
; #define PG8_BAR __builtin_amdgcn_s_barrier()
; #define PG8_SCHED __builtin_amdgcn_sched_barrier(0)
;     ...
;             PG8_LDA(At, 1, 1); PG8_STAGE(PG8_SB(1, 0), b3, voffB); PG8_STAGE(PG8_SB(1, 1), b3 + hstep, voffB); PG8_STAGE(PG8_SA(1, 0), a3, voffA);
;             PG8_WAIT_V(8); PG8_WAIT_L(0); PG8_BAR; PG8_MMA(1, 0, At, B0); PG8_MMA(1, 1, At, B1); PG8_BAR; PG8_SCHED;
;     __device__ __forceinline__ void operator()(const f32x4 (&acc)[2][2][4][2], const pg8::GUnit& u, int wr, int wc, int fr, int fq) const {
;         const int row0 = u.pm * 256 + wr * 64 + fr, col0 = u.pn * 256 + wc * 32 + 8 * fq;
; #pragma unroll
;         for (int ai = 0; ai < 2; ++ai)
; #pragma unroll
;             for (int m = 0; m < 4; ++m) { const size_t row = (size_t)(row0 + ai * 128 + m * 16); float s = 0.f;
; #pragma unroll
;                 for (int bj = 0; bj < 2; ++bj) { const f32x4 v0 = acc[ai][bj][m][0], v1 = acc[ai][bj][m][1];
;                     s += (v0[0] * v0[0] + v0[1] * v0[1]) + (v0[2] * v0[2] + v0[3] * v0[3]) + (v1[0] * v1[0] + v1[1] * v1[1]) + (v1[2] * v1[2] + v1[3] * v1[3]);
;                     u32x4 w; w.x = cvt_pk_bf16(v0[0], v0[1]); w.y = cvt_pk_bf16(v0[2], v0[3]); w.z = cvt_pk_bf16(v1[0], v1[1]); w.w = cvt_pk_bf16(v1[2], v1[3]);
;                     *(GAS u32x4*)((GAS bf16_t*)O + row * DM + col0 + bj * 128) = w; }
;                 { const int ln = fr + 16 * fq; s += __int_as_float(__builtin_amdgcn_ds_bpermute((ln ^ 16) << 2, __float_as_int(s))); s += __int_as_float(__builtin_amdgcn_ds_bpermute((ln ^ 32) << 2, __float_as_int(s))); }
;                 if (fq == 0) ((GAS float*)RSQ)[row * 64 + u.pn * 4 + wc] = s; }
	s_add_i32 s83, s82, 0x80
	ds_read_b128 v[174:177], v145 offset:49152
	ds_read_b128 v[178:181], v145 offset:50176
	ds_read_b128 v[182:185], v145 offset:51200
	ds_read_b128 v[186:189], v145 offset:52224
	ds_read_b128 v[190:193], v145 offset:53248
	ds_read_b128 v[194:197], v145 offset:54272
	ds_read_b128 v[198:201], v145 offset:55296
	ds_read_b128 v[202:205], v145 offset:56320
	s_add_i32 s84, s84, s7
	s_add_i32 vcc_lo, s83, 0x10000000
	s_add_u32 vcc_lo, s100, vcc_lo
	s_addc_u32 vcc_hi, s101, 0
	s_mov_b32 m0, s84
	s_nop 0
	global_load_lds_dwordx4 v141, vcc
	s_add_i32 m0, s84, 0x2000
	s_add_i32 s82, s82, 0x100080
	global_load_lds_dwordx4 v143, vcc
	s_add_i32 s83, s86, s7
	s_add_i32 vcc_lo, s82, 0x10000000
	s_add_u32 vcc_lo, s100, vcc_lo
	s_addc_u32 vcc_hi, s101, 0
	s_mov_b32 m0, s83
	s_nop 0
	global_load_lds_dwordx4 v141, vcc
	s_add_i32 m0, s83, 0x2000
	s_nop 0
	global_load_lds_dwordx4 v143, vcc
	s_mov_b32 m0, s36
	s_add_i32 vcc_lo, s47, 0x10000000
	s_add_u32 vcc_lo, s100, vcc_lo
	s_addc_u32 vcc_hi, s101, 0
	global_load_lds_dwordx4 v140, vcc
	s_mov_b32 m0, s37
	s_nop 0
	global_load_lds_dwordx4 v142, vcc
	s_waitcnt vmcnt(8)
	s_waitcnt lgkmcnt(0)
	s_barrier
	s_setprio 1
	s_waitcnt lgkmcnt(0)
	v_mfma_f32_16x16x32_bf16 v[62:65], v[136:139], v[174:177], v[62:65]
	v_mfma_f32_16x16x32_bf16 v[58:61], v[150:153], v[174:177], v[58:61]
	v_mfma_f32_16x16x32_bf16 v[46:49], v[136:139], v[182:185], v[46:49]
	v_mfma_f32_16x16x32_bf16 v[42:45], v[150:153], v[182:185], v[42:45]
	v_mfma_f32_16x16x32_bf16 v[30:33], v[136:139], v[190:193], v[30:33]
	v_mfma_f32_16x16x32_bf16 v[26:29], v[150:153], v[190:193], v[26:29]
	v_mfma_f32_16x16x32_bf16 v[14:17], v[136:139], v[198:201], v[14:17]
	v_mfma_f32_16x16x32_bf16 v[10:13], v[150:153], v[198:201], v[10:13]
	v_mfma_f32_16x16x32_bf16 v[62:65], v[146:149], v[178:181], v[62:65]
	v_mfma_f32_16x16x32_bf16 v[58:61], v[154:157], v[178:181], v[58:61]
	v_mfma_f32_16x16x32_bf16 v[46:49], v[146:149], v[186:189], v[46:49]
	v_mfma_f32_16x16x32_bf16 v[42:45], v[154:157], v[186:189], v[42:45]
	v_mfma_f32_16x16x32_bf16 v[30:33], v[146:149], v[194:197], v[30:33]
	v_mfma_f32_16x16x32_bf16 v[26:29], v[154:157], v[194:197], v[26:29]
	v_mfma_f32_16x16x32_bf16 v[14:17], v[146:149], v[202:205], v[14:17]
	v_mfma_f32_16x16x32_bf16 v[10:13], v[154:157], v[202:205], v[10:13]
	s_setprio 0
	s_setprio 1
	v_mfma_f32_16x16x32_bf16 v[54:57], v[158:161], v[174:177], v[54:57]
	v_mfma_f32_16x16x32_bf16 v[50:53], v[166:169], v[174:177], v[50:53]
	v_mfma_f32_16x16x32_bf16 v[38:41], v[158:161], v[182:185], v[38:41]
	v_mfma_f32_16x16x32_bf16 v[34:37], v[166:169], v[182:185], v[34:37]
	v_mfma_f32_16x16x32_bf16 v[22:25], v[158:161], v[190:193], v[22:25]
	v_mfma_f32_16x16x32_bf16 v[18:21], v[166:169], v[190:193], v[18:21]
	v_mfma_f32_16x16x32_bf16 v[6:9], v[158:161], v[198:201], v[6:9]
	v_mfma_f32_16x16x32_bf16 v[2:5], v[166:169], v[198:201], v[2:5]
	v_mfma_f32_16x16x32_bf16 v[54:57], v[162:165], v[178:181], v[54:57]
	v_mfma_f32_16x16x32_bf16 v[50:53], v[170:173], v[178:181], v[50:53]
	v_mfma_f32_16x16x32_bf16 v[38:41], v[162:165], v[186:189], v[38:41]
	v_mfma_f32_16x16x32_bf16 v[34:37], v[170:173], v[186:189], v[34:37]
	v_mfma_f32_16x16x32_bf16 v[22:25], v[162:165], v[194:197], v[22:25]
	v_mfma_f32_16x16x32_bf16 v[18:21], v[170:173], v[194:197], v[18:21]
	v_mfma_f32_16x16x32_bf16 v[6:9], v[162:165], v[202:205], v[6:9]
	v_mfma_f32_16x16x32_bf16 v[2:5], v[170:173], v[202:205], v[2:5]
	s_setprio 0
	s_barrier
	s_add_i32 s18, s18, 2
	s_addk_i32 s10, 0x100
	s_addk_i32 s11, 0x100
	s_cmp_gt_u32 s18, 61
	s_cbranch_scc0 .LBB0_862
	s_lshl_b32 s9, s9, 8
	v_mbcnt_lo_u32_b32 v139, -1, 0
	v_mbcnt_hi_u32_b32 v139, -1, v139
	s_add_i32 s9, s9, s3
	v_and_b32_e32 v0, 15, v139
	v_ashrrev_i32_e32 v146, 4, v139
	v_or_b32_e32 v138, s9, v0
	s_lshl_b32 s9, s8, 8
	s_or_b32 s9, s9, s88
	v_lshlrev_b32_e32 v147, 6, v146
	v_lshlrev_b32_e32 v0, 2, v0
	v_lshl_add_u32 v136, v146, 3, s9
	v_bitop3_b32 v146, v147, 64, v0 bitop3:0x36
	v_bitop3_b32 v0, v147, s92, v0 bitop3:0x36
	v_mul_f32_e32 v147, v127, v127
	v_mul_f32_e32 v150, v129, v129
	v_fmac_f32_e32 v147, v126, v126
	v_fmac_f32_e32 v150, v128, v128
	v_add_f32_e32 v147, v147, v150
	v_mul_f32_e32 v150, v123, v123
	v_fmac_f32_e32 v150, v122, v122
	v_cvt_pk_bf16_f32 v126, v126, v127
	v_cvt_pk_bf16_f32 v127, v128, v129
	v_cvt_pk_bf16_f32 v128, v122, v123
	v_mul_f32_e32 v122, v119, v119
	v_mul_f32_e32 v123, v121, v121
	v_fmac_f32_e32 v122, v118, v118
	v_fmac_f32_e32 v123, v120, v120
	v_add_f32_e32 v122, v122, v123
	v_mul_f32_e32 v123, v115, v115
	v_fmac_f32_e32 v123, v114, v114
	v_add_f32_e32 v147, v147, v150
	v_mul_f32_e32 v150, v125, v125
	v_add_f32_e32 v122, v122, v123
	v_mul_f32_e32 v123, v117, v117
	v_fmac_f32_e32 v150, v124, v124
	v_fmac_f32_e32 v123, v116, v116
	v_add_f32_e32 v147, v150, v147
	v_add_f32_e32 v122, v123, v122
	v_cvt_pk_bf16_f32 v129, v124, v125
	v_add_f32_e32 v124, v147, v122
	ds_bpermute_b32 v125, v146, v124
	v_cmp_gt_u32_e32 vcc, 16, v139
	v_ashrrev_i32_e32 v139, 31, v138
	v_lshlrev_b64 v[148:149], 13, v[138:139]
	v_ashrrev_i32_e32 v137, 31, v136
	v_lshl_add_u64 v[122:123], v[132:133], 0, v[148:149]
	v_lshl_add_u64 v[148:149], v[136:137], 1, v[122:123]
	v_cvt_pk_bf16_f32 v122, v118, v119
	s_waitcnt lgkmcnt(0)
	v_add_f32_e32 v118, v124, v125
	ds_bpermute_b32 v119, v0, v118
	s_lshl_b32 s8, s8, 2
	s_ashr_i32 s9, s8, 31
	v_cvt_pk_bf16_f32 v123, v120, v121
	v_cvt_pk_bf16_f32 v124, v114, v115
	v_cvt_pk_bf16_f32 v125, v116, v117
	global_store_dwordx4 v[148:149], v[126:129], off
	global_store_dwordx4 v[148:149], v[122:125], off offset:256
	s_and_saveexec_b64 s[10:11], vcc
	s_cbranch_execz .LBB0_865
	v_lshlrev_b64 v[114:115], 8, v[138:139]
	v_lshl_add_u64 v[114:115], v[134:135], 0, v[114:115]
	v_lshl_add_u64 v[114:115], s[8:9], 2, v[114:115]
	s_lshl_b32 s18, s43, 2
	s_waitcnt lgkmcnt(0)
	v_add_f32_e32 v116, v118, v119
	v_lshl_add_u64 v[114:115], v[114:115], 0, s[18:19]
	global_store_dword v[114:115], v116, off
